# M1 loop header: touch-prefetch of next unit's P32/PSM input lines (loads into a dead VGPR)
# speedup vs baseline: 1.0250x; 1.0250x over previous
; DI void phase_m1(LAS unsigned char* lds, const Params& P, int l) {
;     for (int v = blockIdx.x; v < 512 + 256 + 512 + 512 + 4 * 128; v += gridDim.x) {
;         if (v < 512) prep_delta(lds, P, l, v);
;         else if (v < 768) prep_a_prompt(lds, P, l, v - 512);
;         else if (v < 1280) prep_gla<128, true>(lds, P, l, v - 768);
;         else if (v < 1792) prep_gla<64, false>(lds, P, l, v - 1280);
;         else if (v < 1920) prep_delta_samp(lds, P, l, v - 1792);
;         else if (v < 2048) prep_gla_samp<128, true>(lds, P, l, v - 1920);
;         else if (v < 2176) prep_gla_samp<64, false>(lds, P, l, v - 2048);
;         else prep_a_sample(lds, P, l, v - 2176);
.LBB0_519:
	s_add_i32 s5, s0, s94
	s_cmpk_lt_i32 s5, 0x700
	s_cbranch_scc0 .Ltouch_done
	s_cmpk_lt_i32 s5, 0x200
	s_cbranch_scc0 .Ltouch_not_delta
	s_lshr_b32 s6, s5, 7
	s_bfe_u32 s7, s5, 0x50002
	s_and_b32 s3, s5, 3
	s_lshl_b32 s6, s6, 11
	s_lshl_b32 s7, s7, 6
	s_add_i32 s6, s6, s7
	s_lshl_b32 s3, s3, 9
	s_add_i32 s1, s6, -3
	s_mul_i32 s10, s1, 0x6800
	s_mul_hi_i32 s11, s1, 0x6800
	s_add_u32 s8, s92, s10
	s_addc_u32 s9, s93, s11
	s_add_u32 s8, s8, 0x10064800
	s_addc_u32 s9, s9, 0
	s_add_u32 s8, s8, s3
	s_addc_u32 s9, s9, 0
	v_mov_b32_e32 v16, v197
	v_lshrrev_b32_e32 v18, 3, v16
	v_and_b32_e32 v19, 7, v16
	v_mul_u32_u24_e32 v18, 0x6800, v18
	v_lshl_add_u32 v18, v19, 6, v18
	global_load_dword v206, v18, s[8:9]
	v_add_u32_e32 v16, 0x200, v16
	v_cmp_gt_u32_e32 vcc, 0x218, v16
	v_lshrrev_b32_e32 v18, 3, v16
	v_and_b32_e32 v19, 7, v16
	v_mul_u32_u24_e32 v18, 0x6800, v18
	v_lshl_add_u32 v18, v19, 6, v18
	s_and_saveexec_b64 s[12:13], vcc
	global_load_dword v206, v18, s[8:9]
	s_or_b64 exec, exec, s[12:13]
	s_mul_i32 s10, s1, 0x6800
	s_mul_hi_i32 s11, s1, 0x6800
	s_add_u32 s8, s92, s10
	s_addc_u32 s9, s93, s11
	s_add_u32 s8, s8, 0x10065000
	s_addc_u32 s9, s9, 0
	s_add_u32 s8, s8, s3
	s_addc_u32 s9, s9, 0
	v_mov_b32_e32 v16, v197
	v_lshrrev_b32_e32 v18, 3, v16
	v_and_b32_e32 v19, 7, v16
	v_mul_u32_u24_e32 v18, 0x6800, v18
	v_lshl_add_u32 v18, v19, 6, v18
	global_load_dword v206, v18, s[8:9]
	v_add_u32_e32 v16, 0x200, v16
	v_cmp_gt_u32_e32 vcc, 0x218, v16
	v_lshrrev_b32_e32 v18, 3, v16
	v_and_b32_e32 v19, 7, v16
	v_mul_u32_u24_e32 v18, 0x6800, v18
	v_lshl_add_u32 v18, v19, 6, v18
	s_and_saveexec_b64 s[12:13], vcc
	global_load_dword v206, v18, s[8:9]
	s_or_b64 exec, exec, s[12:13]
	s_mul_i32 s10, s1, 0x6800
	s_mul_hi_i32 s11, s1, 0x6800
	s_add_u32 s8, s92, s10
	s_addc_u32 s9, s93, s11
	s_add_u32 s8, s8, 0x10065800
	s_addc_u32 s9, s9, 0
	s_add_u32 s8, s8, s3
	s_addc_u32 s9, s9, 0
	v_mov_b32_e32 v16, v197
	v_lshrrev_b32_e32 v18, 3, v16
	v_and_b32_e32 v19, 7, v16
	v_mul_u32_u24_e32 v18, 0x6800, v18
	v_lshl_add_u32 v18, v19, 6, v18
	global_load_dword v206, v18, s[8:9]
	v_add_u32_e32 v16, 0x200, v16
	v_cmp_gt_u32_e32 vcc, 0x218, v16
	v_lshrrev_b32_e32 v18, 3, v16
	v_and_b32_e32 v19, 7, v16
	v_mul_u32_u24_e32 v18, 0x6800, v18
	v_lshl_add_u32 v18, v19, 6, v18
	s_and_saveexec_b64 s[12:13], vcc
	global_load_dword v206, v18, s[8:9]
	s_or_b64 exec, exec, s[12:13]
	s_mul_i32 s10, s6, 0x400
	s_mul_hi_i32 s11, s6, 0x400
	s_add_u32 s8, s92, s10
	s_addc_u32 s9, s93, s11
	s_add_u32 s8, s8, 0x1dd60040
	s_addc_u32 s9, s9, 0
	v_mov_b32_e32 v16, v197
	v_cmp_gt_u32_e32 vcc, 0x40, v16
	v_mul_u32_u24_e32 v18, 0x400, v16
	s_and_saveexec_b64 s[12:13], vcc
	global_load_dword v206, v18, s[8:9]
	s_or_b64 exec, exec, s[12:13]
	s_branch .Ltouch_done
.Ltouch_not_delta:
	s_cmpk_lt_i32 s5, 0x300
	s_cbranch_scc0 .Ltouch_not_a
	s_branch .Ltouch_done
.Ltouch_not_a:
	s_cmpk_lt_i32 s5, 0x500
	s_cbranch_scc0 .Ltouch_gla
	s_addk_i32 s5, 0xfd00
	s_lshr_b32 s6, s5, 7
	s_bfe_u32 s7, s5, 0x50002
	s_and_b32 s3, s5, 3
	s_lshl_b32 s6, s6, 11
	s_lshl_b32 s7, s7, 6
	s_add_i32 s6, s6, s7
	s_lshl_b32 s3, s3, 9
	s_mul_i32 s10, s6, 0x6800
	s_mul_hi_i32 s11, s6, 0x6800
	s_add_u32 s8, s92, s10
	s_addc_u32 s9, s93, s11
	s_add_u32 s8, s8, 0x10061800
	s_addc_u32 s9, s9, 0
	s_add_u32 s8, s8, s3
	s_addc_u32 s9, s9, 0
	v_mov_b32_e32 v16, v197
	v_lshrrev_b32_e32 v18, 3, v16
	v_and_b32_e32 v19, 7, v16
	v_mul_u32_u24_e32 v18, 0x6800, v18
	v_lshl_add_u32 v18, v19, 6, v18
	global_load_dword v206, v18, s[8:9]
	s_mul_i32 s10, s6, 0x6800
	s_mul_hi_i32 s11, s6, 0x6800
	s_add_u32 s8, s92, s10
	s_addc_u32 s9, s93, s11
	s_add_u32 s8, s8, 0x10061000
	s_addc_u32 s9, s9, 0
	s_add_u32 s8, s8, s3
	s_addc_u32 s9, s9, 0
	v_mov_b32_e32 v16, v197
	v_lshrrev_b32_e32 v18, 3, v16
	v_and_b32_e32 v19, 7, v16
	v_mul_u32_u24_e32 v18, 0x6800, v18
	v_lshl_add_u32 v18, v19, 6, v18
	global_load_dword v206, v18, s[8:9]
	s_branch .Ltouch_done
.Ltouch_gla:
	s_addk_i32 s5, 0xfb00
	s_lshr_b32 s6, s5, 7
	s_bfe_u32 s7, s5, 0x50002
	s_and_b32 s3, s5, 3
	s_lshl_b32 s6, s6, 11
	s_lshl_b32 s7, s7, 6
	s_add_i32 s6, s6, s7
	s_lshl_b32 s3, s3, 8
	s_mul_i32 s10, s6, 0x6800
	s_mul_hi_i32 s11, s6, 0x6800
	s_add_u32 s8, s92, s10
	s_addc_u32 s9, s93, s11
	s_add_u32 s8, s8, 0x10063000
	s_addc_u32 s9, s9, 0
	s_add_u32 s8, s8, s3
	s_addc_u32 s9, s9, 0
	v_mov_b32_e32 v16, v197
	v_cmp_gt_u32_e32 vcc, 0x100, v16
	v_lshrrev_b32_e32 v18, 2, v16
	v_and_b32_e32 v19, 3, v16
	v_mul_u32_u24_e32 v18, 0x6800, v18
	v_lshl_add_u32 v18, v19, 6, v18
	s_and_saveexec_b64 s[12:13], vcc
	global_load_dword v206, v18, s[8:9]
	s_or_b64 exec, exec, s[12:13]
	s_mul_i32 s10, s6, 0x6800
	s_mul_hi_i32 s11, s6, 0x6800
	s_add_u32 s8, s92, s10
	s_addc_u32 s9, s93, s11
	s_add_u32 s8, s8, 0x10063400
	s_addc_u32 s9, s9, 0
	s_add_u32 s8, s8, s3
	s_addc_u32 s9, s9, 0
	v_mov_b32_e32 v16, v197
	v_cmp_gt_u32_e32 vcc, 0x100, v16
	v_lshrrev_b32_e32 v18, 2, v16
	v_and_b32_e32 v19, 3, v16
	v_mul_u32_u24_e32 v18, 0x6800, v18
	v_lshl_add_u32 v18, v19, 6, v18
	s_and_saveexec_b64 s[12:13], vcc
	global_load_dword v206, v18, s[8:9]
	s_or_b64 exec, exec, s[12:13]
	s_mul_i32 s10, s6, 0x400
	s_mul_hi_i32 s11, s6, 0x400
	s_add_u32 s8, s92, s10
	s_addc_u32 s9, s93, s11
	s_add_u32 s8, s8, 0x1dd60000
	s_addc_u32 s9, s9, 0
	v_mov_b32_e32 v16, v197
	v_cmp_gt_u32_e32 vcc, 0x40, v16
	v_mul_u32_u24_e32 v18, 0x400, v16
	s_and_saveexec_b64 s[12:13], vcc
	global_load_dword v206, v18, s[8:9]
	s_or_b64 exec, exec, s[12:13]

; __device__ __forceinline__ const float* lin(const Params& P, int k) { return P.in[k] + lzero(); }
; DI bf16_t f2bf(float f) { return (bf16_t)(pk2(f, f) & 0xffffu); }
; DI float silu_(float x) { return x * sigm(x); }
; DI void prep_delta(LAS unsigned char* lds, const Params& P, int l, int unit) {
;     ...
;     if (tid < 384) { const int part = tid >> 7, j = tid & 127, ch = part * 512 + up.h * 128 + j;
;         const float* convw = lin(P, 20) + (size_t)l * 4 * 1536;
;         const float w0 = convw[ch], w1 = convw[1536 + ch], w2 = convw[2 * 1536 + ch], w3 = convw[3 * 1536 + ch];
;         float x3, x2, x1;
;         if (up.samp) { const float* cs = lin(P, 5) + (size_t)(l * 128 + up.b) * 3 * 1536; x3 = cs[ch]; x2 = cs[1536 + ch]; x1 = cs[2 * 1536 + ch]; }
;         else if (up.c > 0) { const float* pr = P32 + (size_t)(up.row0 - 3) * LDP + C_DQKV + ch; x3 = pr[0]; x2 = pr[LDP]; x1 = pr[2 * LDP]; }
;         else { x3 = 0.f; x2 = 0.f; x1 = 0.f; }
;         const float* px = P32 + (size_t)up.row0 * LDP + C_DQKV + ch;
;         if (up.samp) {
; #pragma unroll
;             for (int t = 0; t < 16; ++t) { float y = 0.f;
;                 if (t < 4) { const float x0 = px[(size_t)t * LDP]; y = silu_(w0 * x3 + w1 * x2 + w2 * x1 + w3 * x0); x3 = x2; x2 = x1; x1 = x0; }
;                 if (part == 0) qf[t * 136 + j] = f2bf(y); else rhs[t * 256 + (part - 1) * 128 + j] = y; }
;         } else {
; #pragma unroll
;             for (int t = 0; t < 64; ++t) { const float x0 = px[(size_t)t * LDP]; const float y = silu_(w0 * x3 + w1 * x2 + w2 * x1 + w3 * x0); x3 = x2; x2 = x1; x1 = x0;
;                 if (part == 0) qf[t * 136 + j] = f2bf(y); else rhs[t * 256 + (part - 1) * 128 + j] = y; }
.LBB0_843:
	s_mul_hi_i32 s5, s3, 0x6800
	s_mulk_i32 s3, 0x6800
	s_add_u32 s6, s7, s3
	s_addc_u32 s7, s8, s5
	s_add_u32 s6, s6, 0x4800
	s_addc_u32 s7, s7, 0
	v_lshlrev_b32_e32 v18, 2, v2
	v_readfirstlane_b32 s3, v6
	global_load_dword v56, v18, s[6:7]
	s_add_u32 s6, s6, 0x6800
	s_addc_u32 s7, s7, 0
	global_load_dword v57, v18, s[6:7]
	s_add_u32 s6, s6, 0x6800
	s_addc_u32 s7, s7, 0
	global_load_dword v58, v18, s[6:7]
	s_add_u32 s6, s6, 0x6800
	s_addc_u32 s7, s7, 0
	global_load_dword v59, v18, s[6:7]
	s_add_u32 s6, s6, 0x6800
	s_addc_u32 s7, s7, 0
	global_load_dword v60, v18, s[6:7]
	s_add_u32 s6, s6, 0x6800
	s_addc_u32 s7, s7, 0
	global_load_dword v61, v18, s[6:7]
	s_add_u32 s6, s6, 0x6800
	s_addc_u32 s7, s7, 0
	global_load_dword v62, v18, s[6:7]
	s_add_u32 s6, s6, 0x6800
	s_addc_u32 s7, s7, 0
	global_load_dword v63, v18, s[6:7]
	s_add_u32 s6, s6, 0x6800
	s_addc_u32 s7, s7, 0
	global_load_dword v64, v18, s[6:7]
	s_add_u32 s6, s6, 0x6800
	s_addc_u32 s7, s7, 0
	global_load_dword v65, v18, s[6:7]
	s_add_u32 s6, s6, 0x6800
	s_addc_u32 s7, s7, 0
	global_load_dword v66, v18, s[6:7]
	s_add_u32 s6, s6, 0x6800
	s_addc_u32 s7, s7, 0
	global_load_dword v67, v18, s[6:7]
	s_add_u32 s6, s6, 0x6800
	s_addc_u32 s7, s7, 0
	global_load_dword v68, v18, s[6:7]
	s_add_u32 s6, s6, 0x6800
	s_addc_u32 s7, s7, 0
	global_load_dword v69, v18, s[6:7]
	s_add_u32 s6, s6, 0x6800
	s_addc_u32 s7, s7, 0
	global_load_dword v70, v18, s[6:7]
	s_add_u32 s6, s6, 0x6800
	s_addc_u32 s7, s7, 0
	global_load_dword v71, v18, s[6:7]
	s_add_u32 s6, s6, 0x6800
	s_addc_u32 s7, s7, 0
	global_load_dword v72, v18, s[6:7]
	s_add_u32 s6, s6, 0x6800
	s_addc_u32 s7, s7, 0
	global_load_dword v73, v18, s[6:7]
	s_add_u32 s6, s6, 0x6800
	s_addc_u32 s7, s7, 0
	global_load_dword v74, v18, s[6:7]
	s_add_u32 s6, s6, 0x6800
	s_addc_u32 s7, s7, 0
	global_load_dword v75, v18, s[6:7]
	s_add_u32 s6, s6, 0x6800
	s_addc_u32 s7, s7, 0
	global_load_dword v76, v18, s[6:7]
	s_add_u32 s6, s6, 0x6800
	s_addc_u32 s7, s7, 0
	global_load_dword v77, v18, s[6:7]
	s_add_u32 s6, s6, 0x6800
	s_addc_u32 s7, s7, 0
	global_load_dword v78, v18, s[6:7]
	s_add_u32 s6, s6, 0x6800
	s_addc_u32 s7, s7, 0
	global_load_dword v79, v18, s[6:7]
	s_add_u32 s6, s6, 0x6800
	s_addc_u32 s7, s7, 0
	global_load_dword v80, v18, s[6:7]
	s_add_u32 s6, s6, 0x6800
	s_addc_u32 s7, s7, 0
	global_load_dword v81, v18, s[6:7]
	s_add_u32 s6, s6, 0x6800
	s_addc_u32 s7, s7, 0
	global_load_dword v82, v18, s[6:7]
	s_add_u32 s6, s6, 0x6800
	s_addc_u32 s7, s7, 0
	global_load_dword v83, v18, s[6:7]
	s_add_u32 s6, s6, 0x6800
	s_addc_u32 s7, s7, 0
	global_load_dword v84, v18, s[6:7]
	s_add_u32 s6, s6, 0x6800
	s_addc_u32 s7, s7, 0
	global_load_dword v85, v18, s[6:7]
	s_add_u32 s6, s6, 0x6800
	s_addc_u32 s7, s7, 0
	global_load_dword v86, v18, s[6:7]
	s_add_u32 s6, s6, 0x6800
	s_addc_u32 s7, s7, 0
	global_load_dword v87, v18, s[6:7]
	s_add_u32 s6, s6, 0x6800
	s_addc_u32 s7, s7, 0
	global_load_dword v88, v18, s[6:7]
	s_add_u32 s6, s6, 0x6800
	s_addc_u32 s7, s7, 0
	global_load_dword v89, v18, s[6:7]
	s_add_u32 s6, s6, 0x6800
	s_addc_u32 s7, s7, 0
	global_load_dword v90, v18, s[6:7]
	s_add_u32 s6, s6, 0x6800
	s_addc_u32 s7, s7, 0
	global_load_dword v91, v18, s[6:7]
	s_add_u32 s6, s6, 0x6800
	s_addc_u32 s7, s7, 0
	global_load_dword v92, v18, s[6:7]
	s_add_u32 s6, s6, 0x6800
	s_addc_u32 s7, s7, 0
	global_load_dword v93, v18, s[6:7]
	s_add_u32 s6, s6, 0x6800
	s_addc_u32 s7, s7, 0
	global_load_dword v94, v18, s[6:7]
	s_add_u32 s6, s6, 0x6800
	s_addc_u32 s7, s7, 0
	global_load_dword v95, v18, s[6:7]
	s_add_u32 s6, s6, 0x6800
	s_addc_u32 s7, s7, 0
	s_cmpk_gt_u32 s3, 0x7f
	s_cbranch_scc1 .Lconv_rhs_part
	v_lshlrev_b32_e32 v19, 1, v0
	v_add_u32_e32 v19, 0x14500, v19
	s_waitcnt vmcnt(36)
	v_mul_f32_e32 v20, v4, v10
	v_mul_f32_e32 v21, v4, v11
	v_mul_f32_e32 v22, v4, v15
	v_mul_f32_e32 v23, v4, v56
	v_fmac_f32_e32 v20, v5, v11
	v_fmac_f32_e32 v21, v5, v15
	v_fmac_f32_e32 v22, v5, v56
	v_fmac_f32_e32 v23, v5, v57
	v_fmac_f32_e32 v20, v7, v15
	v_fmac_f32_e32 v21, v7, v56
	v_fmac_f32_e32 v22, v7, v57
	v_fmac_f32_e32 v23, v7, v58
	v_fmac_f32_e32 v20, v9, v56
	v_fmac_f32_e32 v21, v9, v57
	v_fmac_f32_e32 v22, v9, v58
	v_fmac_f32_e32 v23, v9, v59
	v_mul_f32_e32 v24, 0xbfb8aa3b, v20
	v_mul_f32_e32 v25, 0xbfb8aa3b, v21
	v_mul_f32_e32 v26, 0xbfb8aa3b, v22
	v_mul_f32_e32 v27, 0xbfb8aa3b, v23
	v_exp_f32_e32 v24, v24
	v_exp_f32_e32 v25, v25
	v_exp_f32_e32 v26, v26
	v_exp_f32_e32 v27, v27
	v_add_f32_e32 v24, 1.0, v24
	v_add_f32_e32 v25, 1.0, v25
	v_add_f32_e32 v26, 1.0, v26
	v_add_f32_e32 v27, 1.0, v27
	v_rcp_f32_e32 v24, v24
	v_rcp_f32_e32 v25, v25
	v_rcp_f32_e32 v26, v26
	v_rcp_f32_e32 v27, v27
	v_mul_f32_e32 v20, v20, v24
	v_mul_f32_e32 v21, v21, v25
	v_mul_f32_e32 v22, v22, v26
	v_mul_f32_e32 v23, v23, v27
	v_cvt_pk_bf16_f32 v20, v20, v20
	v_cvt_pk_bf16_f32 v21, v21, v21
	v_cvt_pk_bf16_f32 v22, v22, v22
	v_cvt_pk_bf16_f32 v23, v23, v23
	ds_write_b16 v19, v20 offset:0
	ds_write_b16 v19, v21 offset:272
	ds_write_b16 v19, v22 offset:544
	ds_write_b16 v19, v23 offset:816
	s_waitcnt vmcnt(32)
; DI bf16_t f2bf(float f) { return (bf16_t)(pk2(f, f) & 0xffffu); }
; DI float silu_(float x) { return x * sigm(x); }
; DI void prep_delta(LAS unsigned char* lds, const Params& P, int l, int unit) {
;     ...
; #pragma unroll
;             for (int t = 0; t < 64; ++t) { const float x0 = px[(size_t)t * LDP]; const float y = silu_(w0 * x3 + w1 * x2 + w2 * x1 + w3 * x0); x3 = x2; x2 = x1; x1 = x0;
;                 if (part == 0) qf[t * 136 + j] = f2bf(y); else rhs[t * 256 + (part - 1) * 128 + j] = y; }
	v_mul_f32_e32 v20, v4, v57
	v_mul_f32_e32 v21, v4, v58
	v_mul_f32_e32 v22, v4, v59
	v_mul_f32_e32 v23, v4, v60
	v_fmac_f32_e32 v20, v5, v58
	v_fmac_f32_e32 v21, v5, v59
	v_fmac_f32_e32 v22, v5, v60
	v_fmac_f32_e32 v23, v5, v61
	v_fmac_f32_e32 v20, v7, v59
	v_fmac_f32_e32 v21, v7, v60
	v_fmac_f32_e32 v22, v7, v61
	v_fmac_f32_e32 v23, v7, v62
	v_fmac_f32_e32 v20, v9, v60
	v_fmac_f32_e32 v21, v9, v61
	v_fmac_f32_e32 v22, v9, v62
	v_fmac_f32_e32 v23, v9, v63
	v_mul_f32_e32 v24, 0xbfb8aa3b, v20
	v_mul_f32_e32 v25, 0xbfb8aa3b, v21
	v_mul_f32_e32 v26, 0xbfb8aa3b, v22
	v_mul_f32_e32 v27, 0xbfb8aa3b, v23
	v_exp_f32_e32 v24, v24
	v_exp_f32_e32 v25, v25
	v_exp_f32_e32 v26, v26
	v_exp_f32_e32 v27, v27
	v_add_f32_e32 v24, 1.0, v24
	v_add_f32_e32 v25, 1.0, v25
	v_add_f32_e32 v26, 1.0, v26
	v_add_f32_e32 v27, 1.0, v27
	v_rcp_f32_e32 v24, v24
	v_rcp_f32_e32 v25, v25
	v_rcp_f32_e32 v26, v26
	v_rcp_f32_e32 v27, v27
	v_mul_f32_e32 v20, v20, v24
	v_mul_f32_e32 v21, v21, v25
	v_mul_f32_e32 v22, v22, v26
	v_mul_f32_e32 v23, v23, v27
	v_cvt_pk_bf16_f32 v20, v20, v20
	v_cvt_pk_bf16_f32 v21, v21, v21
	v_cvt_pk_bf16_f32 v22, v22, v22
	v_cvt_pk_bf16_f32 v23, v23, v23
	ds_write_b16 v19, v20 offset:1088
	ds_write_b16 v19, v21 offset:1360
	ds_write_b16 v19, v22 offset:1632
	ds_write_b16 v19, v23 offset:1904
	s_waitcnt vmcnt(28)
	v_mul_f32_e32 v20, v4, v61
	v_mul_f32_e32 v21, v4, v62
	v_mul_f32_e32 v22, v4, v63
	v_mul_f32_e32 v23, v4, v64
	v_fmac_f32_e32 v20, v5, v62
	v_fmac_f32_e32 v21, v5, v63
	v_fmac_f32_e32 v22, v5, v64
	v_fmac_f32_e32 v23, v5, v65
	v_fmac_f32_e32 v20, v7, v63
	v_fmac_f32_e32 v21, v7, v64
	v_fmac_f32_e32 v22, v7, v65
	v_fmac_f32_e32 v23, v7, v66
	v_fmac_f32_e32 v20, v9, v64
	v_fmac_f32_e32 v21, v9, v65
	v_fmac_f32_e32 v22, v9, v66
	v_fmac_f32_e32 v23, v9, v67
	v_mul_f32_e32 v24, 0xbfb8aa3b, v20
	v_mul_f32_e32 v25, 0xbfb8aa3b, v21
	v_mul_f32_e32 v26, 0xbfb8aa3b, v22
	v_mul_f32_e32 v27, 0xbfb8aa3b, v23
	v_exp_f32_e32 v24, v24
	v_exp_f32_e32 v25, v25
	v_exp_f32_e32 v26, v26
	v_exp_f32_e32 v27, v27
	v_add_f32_e32 v24, 1.0, v24
	v_add_f32_e32 v25, 1.0, v25
	v_add_f32_e32 v26, 1.0, v26
	v_add_f32_e32 v27, 1.0, v27
	v_rcp_f32_e32 v24, v24
	v_rcp_f32_e32 v25, v25
	v_rcp_f32_e32 v26, v26
	v_rcp_f32_e32 v27, v27
	v_mul_f32_e32 v20, v20, v24
	v_mul_f32_e32 v21, v21, v25
	v_mul_f32_e32 v22, v22, v26
	v_mul_f32_e32 v23, v23, v27
	v_cvt_pk_bf16_f32 v20, v20, v20
	v_cvt_pk_bf16_f32 v21, v21, v21
	v_cvt_pk_bf16_f32 v22, v22, v22
	v_cvt_pk_bf16_f32 v23, v23, v23
	ds_write_b16 v19, v20 offset:2176
	ds_write_b16 v19, v21 offset:2448
	ds_write_b16 v19, v22 offset:2720
	ds_write_b16 v19, v23 offset:2992
	s_waitcnt vmcnt(24)
	v_mul_f32_e32 v20, v4, v65
	v_mul_f32_e32 v21, v4, v66
	v_mul_f32_e32 v22, v4, v67
	v_mul_f32_e32 v23, v4, v68
	v_fmac_f32_e32 v20, v5, v66
	v_fmac_f32_e32 v21, v5, v67
	v_fmac_f32_e32 v22, v5, v68
	v_fmac_f32_e32 v23, v5, v69
	v_fmac_f32_e32 v20, v7, v67
	v_fmac_f32_e32 v21, v7, v68
	v_fmac_f32_e32 v22, v7, v69
	v_fmac_f32_e32 v23, v7, v70
	v_fmac_f32_e32 v20, v9, v68
	v_fmac_f32_e32 v21, v9, v69
	v_fmac_f32_e32 v22, v9, v70
	v_fmac_f32_e32 v23, v9, v71
	v_mul_f32_e32 v24, 0xbfb8aa3b, v20
	v_mul_f32_e32 v25, 0xbfb8aa3b, v21
	v_mul_f32_e32 v26, 0xbfb8aa3b, v22
	v_mul_f32_e32 v27, 0xbfb8aa3b, v23
	v_exp_f32_e32 v24, v24
	v_exp_f32_e32 v25, v25
	v_exp_f32_e32 v26, v26
	v_exp_f32_e32 v27, v27
	v_add_f32_e32 v24, 1.0, v24
	v_add_f32_e32 v25, 1.0, v25
	v_add_f32_e32 v26, 1.0, v26
	v_add_f32_e32 v27, 1.0, v27
	v_rcp_f32_e32 v24, v24
	v_rcp_f32_e32 v25, v25
	v_rcp_f32_e32 v26, v26
	v_rcp_f32_e32 v27, v27
	v_mul_f32_e32 v20, v20, v24
	v_mul_f32_e32 v21, v21, v25
	v_mul_f32_e32 v22, v22, v26
	v_mul_f32_e32 v23, v23, v27
	v_cvt_pk_bf16_f32 v20, v20, v20
	v_cvt_pk_bf16_f32 v21, v21, v21
	v_cvt_pk_bf16_f32 v22, v22, v22
	v_cvt_pk_bf16_f32 v23, v23, v23
	ds_write_b16 v19, v20 offset:3264
	ds_write_b16 v19, v21 offset:3536
	ds_write_b16 v19, v22 offset:3808
	ds_write_b16 v19, v23 offset:4080
	global_load_dword v96, v18, s[6:7]
	s_add_u32 s6, s6, 0x6800
	s_addc_u32 s7, s7, 0
	global_load_dword v97, v18, s[6:7]
	s_add_u32 s6, s6, 0x6800
	s_addc_u32 s7, s7, 0
	global_load_dword v98, v18, s[6:7]
	s_add_u32 s6, s6, 0x6800
	s_addc_u32 s7, s7, 0
	global_load_dword v99, v18, s[6:7]
	s_add_u32 s6, s6, 0x6800
	s_addc_u32 s7, s7, 0
	global_load_dword v100, v18, s[6:7]
	s_add_u32 s6, s6, 0x6800
	s_addc_u32 s7, s7, 0
	global_load_dword v101, v18, s[6:7]
	s_add_u32 s6, s6, 0x6800
	s_addc_u32 s7, s7, 0
	global_load_dword v102, v18, s[6:7]
	s_add_u32 s6, s6, 0x6800
	s_addc_u32 s7, s7, 0
	global_load_dword v103, v18, s[6:7]
	s_add_u32 s6, s6, 0x6800
	s_addc_u32 s7, s7, 0
	global_load_dword v104, v18, s[6:7]
	s_add_u32 s6, s6, 0x6800
	s_addc_u32 s7, s7, 0
	global_load_dword v105, v18, s[6:7]
	s_add_u32 s6, s6, 0x6800
	s_addc_u32 s7, s7, 0
	global_load_dword v106, v18, s[6:7]
	s_add_u32 s6, s6, 0x6800
	s_addc_u32 s7, s7, 0
	global_load_dword v107, v18, s[6:7]
	s_add_u32 s6, s6, 0x6800
	s_addc_u32 s7, s7, 0
	global_load_dword v108, v18, s[6:7]
	s_add_u32 s6, s6, 0x6800
	s_addc_u32 s7, s7, 0
	global_load_dword v109, v18, s[6:7]
	s_add_u32 s6, s6, 0x6800
	s_addc_u32 s7, s7, 0
	global_load_dword v110, v18, s[6:7]
	s_add_u32 s6, s6, 0x6800
	s_addc_u32 s7, s7, 0
	global_load_dword v111, v18, s[6:7]
	s_add_u32 s6, s6, 0x6800
	s_addc_u32 s7, s7, 0
	global_load_dword v112, v18, s[6:7]
	s_add_u32 s6, s6, 0x6800
	s_addc_u32 s7, s7, 0
	global_load_dword v113, v18, s[6:7]
	s_add_u32 s6, s6, 0x6800
	s_addc_u32 s7, s7, 0
	global_load_dword v114, v18, s[6:7]
	s_add_u32 s6, s6, 0x6800
	s_addc_u32 s7, s7, 0
	global_load_dword v115, v18, s[6:7]
	s_add_u32 s6, s6, 0x6800
	s_addc_u32 s7, s7, 0
	global_load_dword v116, v18, s[6:7]
	s_add_u32 s6, s6, 0x6800
	s_addc_u32 s7, s7, 0
	global_load_dword v117, v18, s[6:7]
	s_add_u32 s6, s6, 0x6800
	s_addc_u32 s7, s7, 0
	global_load_dword v118, v18, s[6:7]
	s_add_u32 s6, s6, 0x6800
	s_addc_u32 s7, s7, 0
	global_load_dword v119, v18, s[6:7]
	s_add_u32 s6, s6, 0x6800
	s_addc_u32 s7, s7, 0
	s_waitcnt vmcnt(44)
; DI bf16_t f2bf(float f) { return (bf16_t)(pk2(f, f) & 0xffffu); }
; DI float silu_(float x) { return x * sigm(x); }
; DI void prep_delta(LAS unsigned char* lds, const Params& P, int l, int unit) {
;     ...
; #pragma unroll
;             for (int t = 0; t < 64; ++t) { const float x0 = px[(size_t)t * LDP]; const float y = silu_(w0 * x3 + w1 * x2 + w2 * x1 + w3 * x0); x3 = x2; x2 = x1; x1 = x0;
;                 if (part == 0) qf[t * 136 + j] = f2bf(y); else rhs[t * 256 + (part - 1) * 128 + j] = y; }
	v_mul_f32_e32 v20, v4, v69
	v_mul_f32_e32 v21, v4, v70
	v_mul_f32_e32 v22, v4, v71
	v_mul_f32_e32 v23, v4, v72
	v_fmac_f32_e32 v20, v5, v70
	v_fmac_f32_e32 v21, v5, v71
	v_fmac_f32_e32 v22, v5, v72
	v_fmac_f32_e32 v23, v5, v73
	v_fmac_f32_e32 v20, v7, v71
	v_fmac_f32_e32 v21, v7, v72
	v_fmac_f32_e32 v22, v7, v73
	v_fmac_f32_e32 v23, v7, v74
	v_fmac_f32_e32 v20, v9, v72
	v_fmac_f32_e32 v21, v9, v73
	v_fmac_f32_e32 v22, v9, v74
	v_fmac_f32_e32 v23, v9, v75
	v_mul_f32_e32 v24, 0xbfb8aa3b, v20
	v_mul_f32_e32 v25, 0xbfb8aa3b, v21
	v_mul_f32_e32 v26, 0xbfb8aa3b, v22
	v_mul_f32_e32 v27, 0xbfb8aa3b, v23
	v_exp_f32_e32 v24, v24
	v_exp_f32_e32 v25, v25
	v_exp_f32_e32 v26, v26
	v_exp_f32_e32 v27, v27
	v_add_f32_e32 v24, 1.0, v24
	v_add_f32_e32 v25, 1.0, v25
	v_add_f32_e32 v26, 1.0, v26
	v_add_f32_e32 v27, 1.0, v27
	v_rcp_f32_e32 v24, v24
	v_rcp_f32_e32 v25, v25
	v_rcp_f32_e32 v26, v26
	v_rcp_f32_e32 v27, v27
	v_mul_f32_e32 v20, v20, v24
	v_mul_f32_e32 v21, v21, v25
	v_mul_f32_e32 v22, v22, v26
	v_mul_f32_e32 v23, v23, v27
	v_cvt_pk_bf16_f32 v20, v20, v20
	v_cvt_pk_bf16_f32 v21, v21, v21
	v_cvt_pk_bf16_f32 v22, v22, v22
	v_cvt_pk_bf16_f32 v23, v23, v23
	ds_write_b16 v19, v20 offset:4352
	ds_write_b16 v19, v21 offset:4624
	ds_write_b16 v19, v22 offset:4896
	ds_write_b16 v19, v23 offset:5168
	s_waitcnt vmcnt(40)
	v_mul_f32_e32 v20, v4, v73
	v_mul_f32_e32 v21, v4, v74
	v_mul_f32_e32 v22, v4, v75
	v_mul_f32_e32 v23, v4, v76
	v_fmac_f32_e32 v20, v5, v74
	v_fmac_f32_e32 v21, v5, v75
	v_fmac_f32_e32 v22, v5, v76
	v_fmac_f32_e32 v23, v5, v77
	v_fmac_f32_e32 v20, v7, v75
	v_fmac_f32_e32 v21, v7, v76
	v_fmac_f32_e32 v22, v7, v77
	v_fmac_f32_e32 v23, v7, v78
	v_fmac_f32_e32 v20, v9, v76
	v_fmac_f32_e32 v21, v9, v77
	v_fmac_f32_e32 v22, v9, v78
	v_fmac_f32_e32 v23, v9, v79
	v_mul_f32_e32 v24, 0xbfb8aa3b, v20
	v_mul_f32_e32 v25, 0xbfb8aa3b, v21
	v_mul_f32_e32 v26, 0xbfb8aa3b, v22
	v_mul_f32_e32 v27, 0xbfb8aa3b, v23
	v_exp_f32_e32 v24, v24
	v_exp_f32_e32 v25, v25
	v_exp_f32_e32 v26, v26
	v_exp_f32_e32 v27, v27
	v_add_f32_e32 v24, 1.0, v24
	v_add_f32_e32 v25, 1.0, v25
	v_add_f32_e32 v26, 1.0, v26
	v_add_f32_e32 v27, 1.0, v27
	v_rcp_f32_e32 v24, v24
	v_rcp_f32_e32 v25, v25
	v_rcp_f32_e32 v26, v26
	v_rcp_f32_e32 v27, v27
	v_mul_f32_e32 v20, v20, v24
	v_mul_f32_e32 v21, v21, v25
	v_mul_f32_e32 v22, v22, v26
	v_mul_f32_e32 v23, v23, v27
	v_cvt_pk_bf16_f32 v20, v20, v20
	v_cvt_pk_bf16_f32 v21, v21, v21
	v_cvt_pk_bf16_f32 v22, v22, v22
	v_cvt_pk_bf16_f32 v23, v23, v23
	ds_write_b16 v19, v20 offset:5440
	ds_write_b16 v19, v21 offset:5712
	ds_write_b16 v19, v22 offset:5984
	ds_write_b16 v19, v23 offset:6256
	s_waitcnt vmcnt(36)
	v_mul_f32_e32 v20, v4, v77
	v_mul_f32_e32 v21, v4, v78
	v_mul_f32_e32 v22, v4, v79
	v_mul_f32_e32 v23, v4, v80
	v_fmac_f32_e32 v20, v5, v78
	v_fmac_f32_e32 v21, v5, v79
	v_fmac_f32_e32 v22, v5, v80
	v_fmac_f32_e32 v23, v5, v81
	v_fmac_f32_e32 v20, v7, v79
	v_fmac_f32_e32 v21, v7, v80
	v_fmac_f32_e32 v22, v7, v81
	v_fmac_f32_e32 v23, v7, v82
	v_fmac_f32_e32 v20, v9, v80
	v_fmac_f32_e32 v21, v9, v81
	v_fmac_f32_e32 v22, v9, v82
	v_fmac_f32_e32 v23, v9, v83
	v_mul_f32_e32 v24, 0xbfb8aa3b, v20
	v_mul_f32_e32 v25, 0xbfb8aa3b, v21
	v_mul_f32_e32 v26, 0xbfb8aa3b, v22
	v_mul_f32_e32 v27, 0xbfb8aa3b, v23
	v_exp_f32_e32 v24, v24
	v_exp_f32_e32 v25, v25
	v_exp_f32_e32 v26, v26
	v_exp_f32_e32 v27, v27
	v_add_f32_e32 v24, 1.0, v24
	v_add_f32_e32 v25, 1.0, v25
	v_add_f32_e32 v26, 1.0, v26
	v_add_f32_e32 v27, 1.0, v27
	v_rcp_f32_e32 v24, v24
	v_rcp_f32_e32 v25, v25
	v_rcp_f32_e32 v26, v26
	v_rcp_f32_e32 v27, v27
	v_mul_f32_e32 v20, v20, v24
	v_mul_f32_e32 v21, v21, v25
	v_mul_f32_e32 v22, v22, v26
	v_mul_f32_e32 v23, v23, v27
	v_cvt_pk_bf16_f32 v20, v20, v20
	v_cvt_pk_bf16_f32 v21, v21, v21
	v_cvt_pk_bf16_f32 v22, v22, v22
	v_cvt_pk_bf16_f32 v23, v23, v23
	ds_write_b16 v19, v20 offset:6528
	ds_write_b16 v19, v21 offset:6800
	ds_write_b16 v19, v22 offset:7072
	ds_write_b16 v19, v23 offset:7344
	s_waitcnt vmcnt(32)
	v_mul_f32_e32 v20, v4, v81
	v_mul_f32_e32 v21, v4, v82
	v_mul_f32_e32 v22, v4, v83
	v_mul_f32_e32 v23, v4, v84
	v_fmac_f32_e32 v20, v5, v82
	v_fmac_f32_e32 v21, v5, v83
	v_fmac_f32_e32 v22, v5, v84
	v_fmac_f32_e32 v23, v5, v85
	v_fmac_f32_e32 v20, v7, v83
	v_fmac_f32_e32 v21, v7, v84
	v_fmac_f32_e32 v22, v7, v85
	v_fmac_f32_e32 v23, v7, v86
	v_fmac_f32_e32 v20, v9, v84
	v_fmac_f32_e32 v21, v9, v85
	v_fmac_f32_e32 v22, v9, v86
	v_fmac_f32_e32 v23, v9, v87
	v_mul_f32_e32 v24, 0xbfb8aa3b, v20
	v_mul_f32_e32 v25, 0xbfb8aa3b, v21
	v_mul_f32_e32 v26, 0xbfb8aa3b, v22
	v_mul_f32_e32 v27, 0xbfb8aa3b, v23
	v_exp_f32_e32 v24, v24
	v_exp_f32_e32 v25, v25
	v_exp_f32_e32 v26, v26
	v_exp_f32_e32 v27, v27
	v_add_f32_e32 v24, 1.0, v24
	v_add_f32_e32 v25, 1.0, v25
	v_add_f32_e32 v26, 1.0, v26
	v_add_f32_e32 v27, 1.0, v27
	v_rcp_f32_e32 v24, v24
	v_rcp_f32_e32 v25, v25
	v_rcp_f32_e32 v26, v26
	v_rcp_f32_e32 v27, v27
	v_mul_f32_e32 v20, v20, v24
	v_mul_f32_e32 v21, v21, v25
	v_mul_f32_e32 v22, v22, v26
	v_mul_f32_e32 v23, v23, v27
	v_cvt_pk_bf16_f32 v20, v20, v20
	v_cvt_pk_bf16_f32 v21, v21, v21
	v_cvt_pk_bf16_f32 v22, v22, v22
	v_cvt_pk_bf16_f32 v23, v23, v23
	ds_write_b16 v19, v20 offset:7616
	ds_write_b16 v19, v21 offset:7888
	ds_write_b16 v19, v22 offset:8160
	ds_write_b16 v19, v23 offset:8432
	s_waitcnt vmcnt(28)
; DI bf16_t f2bf(float f) { return (bf16_t)(pk2(f, f) & 0xffffu); }
; DI float silu_(float x) { return x * sigm(x); }
; DI void prep_delta(LAS unsigned char* lds, const Params& P, int l, int unit) {
;     ...
; #pragma unroll
;             for (int t = 0; t < 64; ++t) { const float x0 = px[(size_t)t * LDP]; const float y = silu_(w0 * x3 + w1 * x2 + w2 * x1 + w3 * x0); x3 = x2; x2 = x1; x1 = x0;
;                 if (part == 0) qf[t * 136 + j] = f2bf(y); else rhs[t * 256 + (part - 1) * 128 + j] = y; }
	v_mul_f32_e32 v20, v4, v85
	v_mul_f32_e32 v21, v4, v86
	v_mul_f32_e32 v22, v4, v87
	v_mul_f32_e32 v23, v4, v88
	v_fmac_f32_e32 v20, v5, v86
	v_fmac_f32_e32 v21, v5, v87
	v_fmac_f32_e32 v22, v5, v88
	v_fmac_f32_e32 v23, v5, v89
	v_fmac_f32_e32 v20, v7, v87
	v_fmac_f32_e32 v21, v7, v88
	v_fmac_f32_e32 v22, v7, v89
	v_fmac_f32_e32 v23, v7, v90
	v_fmac_f32_e32 v20, v9, v88
	v_fmac_f32_e32 v21, v9, v89
	v_fmac_f32_e32 v22, v9, v90
	v_fmac_f32_e32 v23, v9, v91
	v_mul_f32_e32 v24, 0xbfb8aa3b, v20
	v_mul_f32_e32 v25, 0xbfb8aa3b, v21
	v_mul_f32_e32 v26, 0xbfb8aa3b, v22
	v_mul_f32_e32 v27, 0xbfb8aa3b, v23
	v_exp_f32_e32 v24, v24
	v_exp_f32_e32 v25, v25
	v_exp_f32_e32 v26, v26
	v_exp_f32_e32 v27, v27
	v_add_f32_e32 v24, 1.0, v24
	v_add_f32_e32 v25, 1.0, v25
	v_add_f32_e32 v26, 1.0, v26
	v_add_f32_e32 v27, 1.0, v27
	v_rcp_f32_e32 v24, v24
	v_rcp_f32_e32 v25, v25
	v_rcp_f32_e32 v26, v26
	v_rcp_f32_e32 v27, v27
	v_mul_f32_e32 v20, v20, v24
	v_mul_f32_e32 v21, v21, v25
	v_mul_f32_e32 v22, v22, v26
	v_mul_f32_e32 v23, v23, v27
	v_cvt_pk_bf16_f32 v20, v20, v20
	v_cvt_pk_bf16_f32 v21, v21, v21
	v_cvt_pk_bf16_f32 v22, v22, v22
	v_cvt_pk_bf16_f32 v23, v23, v23
	ds_write_b16 v19, v20 offset:8704
	ds_write_b16 v19, v21 offset:8976
	ds_write_b16 v19, v22 offset:9248
	ds_write_b16 v19, v23 offset:9520
	s_waitcnt vmcnt(24)
	v_mul_f32_e32 v20, v4, v89
	v_mul_f32_e32 v21, v4, v90
	v_mul_f32_e32 v22, v4, v91
	v_mul_f32_e32 v23, v4, v92
	v_fmac_f32_e32 v20, v5, v90
	v_fmac_f32_e32 v21, v5, v91
	v_fmac_f32_e32 v22, v5, v92
	v_fmac_f32_e32 v23, v5, v93
	v_fmac_f32_e32 v20, v7, v91
	v_fmac_f32_e32 v21, v7, v92
	v_fmac_f32_e32 v22, v7, v93
	v_fmac_f32_e32 v23, v7, v94
	v_fmac_f32_e32 v20, v9, v92
	v_fmac_f32_e32 v21, v9, v93
	v_fmac_f32_e32 v22, v9, v94
	v_fmac_f32_e32 v23, v9, v95
	v_mul_f32_e32 v24, 0xbfb8aa3b, v20
	v_mul_f32_e32 v25, 0xbfb8aa3b, v21
	v_mul_f32_e32 v26, 0xbfb8aa3b, v22
	v_mul_f32_e32 v27, 0xbfb8aa3b, v23
	v_exp_f32_e32 v24, v24
	v_exp_f32_e32 v25, v25
	v_exp_f32_e32 v26, v26
	v_exp_f32_e32 v27, v27
	v_add_f32_e32 v24, 1.0, v24
	v_add_f32_e32 v25, 1.0, v25
	v_add_f32_e32 v26, 1.0, v26
	v_add_f32_e32 v27, 1.0, v27
	v_rcp_f32_e32 v24, v24
	v_rcp_f32_e32 v25, v25
	v_rcp_f32_e32 v26, v26
	v_rcp_f32_e32 v27, v27
	v_mul_f32_e32 v20, v20, v24
	v_mul_f32_e32 v21, v21, v25
	v_mul_f32_e32 v22, v22, v26
	v_mul_f32_e32 v23, v23, v27
	v_cvt_pk_bf16_f32 v20, v20, v20
	v_cvt_pk_bf16_f32 v21, v21, v21
	v_cvt_pk_bf16_f32 v22, v22, v22
	v_cvt_pk_bf16_f32 v23, v23, v23
	ds_write_b16 v19, v20 offset:9792
	ds_write_b16 v19, v21 offset:10064
	ds_write_b16 v19, v22 offset:10336
	ds_write_b16 v19, v23 offset:10608
	s_waitcnt vmcnt(20)
	v_mul_f32_e32 v20, v4, v93
	v_mul_f32_e32 v21, v4, v94
	v_mul_f32_e32 v22, v4, v95
	v_mul_f32_e32 v23, v4, v96
	v_fmac_f32_e32 v20, v5, v94
	v_fmac_f32_e32 v21, v5, v95
	v_fmac_f32_e32 v22, v5, v96
	v_fmac_f32_e32 v23, v5, v97
	v_fmac_f32_e32 v20, v7, v95
	v_fmac_f32_e32 v21, v7, v96
	v_fmac_f32_e32 v22, v7, v97
	v_fmac_f32_e32 v23, v7, v98
	v_fmac_f32_e32 v20, v9, v96
	v_fmac_f32_e32 v21, v9, v97
	v_fmac_f32_e32 v22, v9, v98
	v_fmac_f32_e32 v23, v9, v99
	v_mul_f32_e32 v24, 0xbfb8aa3b, v20
	v_mul_f32_e32 v25, 0xbfb8aa3b, v21
	v_mul_f32_e32 v26, 0xbfb8aa3b, v22
	v_mul_f32_e32 v27, 0xbfb8aa3b, v23
	v_exp_f32_e32 v24, v24
	v_exp_f32_e32 v25, v25
	v_exp_f32_e32 v26, v26
	v_exp_f32_e32 v27, v27
	v_add_f32_e32 v24, 1.0, v24
	v_add_f32_e32 v25, 1.0, v25
	v_add_f32_e32 v26, 1.0, v26
	v_add_f32_e32 v27, 1.0, v27
	v_rcp_f32_e32 v24, v24
	v_rcp_f32_e32 v25, v25
	v_rcp_f32_e32 v26, v26
	v_rcp_f32_e32 v27, v27
	v_mul_f32_e32 v20, v20, v24
	v_mul_f32_e32 v21, v21, v25
	v_mul_f32_e32 v22, v22, v26
	v_mul_f32_e32 v23, v23, v27
	v_cvt_pk_bf16_f32 v20, v20, v20
	v_cvt_pk_bf16_f32 v21, v21, v21
	v_cvt_pk_bf16_f32 v22, v22, v22
	v_cvt_pk_bf16_f32 v23, v23, v23
	ds_write_b16 v19, v20 offset:10880
	ds_write_b16 v19, v21 offset:11152
	ds_write_b16 v19, v22 offset:11424
	ds_write_b16 v19, v23 offset:11696
	s_waitcnt vmcnt(16)
	v_mul_f32_e32 v20, v4, v97
	v_mul_f32_e32 v21, v4, v98
	v_mul_f32_e32 v22, v4, v99
	v_mul_f32_e32 v23, v4, v100
	v_fmac_f32_e32 v20, v5, v98
	v_fmac_f32_e32 v21, v5, v99
	v_fmac_f32_e32 v22, v5, v100
	v_fmac_f32_e32 v23, v5, v101
	v_fmac_f32_e32 v20, v7, v99
	v_fmac_f32_e32 v21, v7, v100
	v_fmac_f32_e32 v22, v7, v101
	v_fmac_f32_e32 v23, v7, v102
	v_fmac_f32_e32 v20, v9, v100
	v_fmac_f32_e32 v21, v9, v101
	v_fmac_f32_e32 v22, v9, v102
	v_fmac_f32_e32 v23, v9, v103
	v_mul_f32_e32 v24, 0xbfb8aa3b, v20
	v_mul_f32_e32 v25, 0xbfb8aa3b, v21
	v_mul_f32_e32 v26, 0xbfb8aa3b, v22
	v_mul_f32_e32 v27, 0xbfb8aa3b, v23
	v_exp_f32_e32 v24, v24
	v_exp_f32_e32 v25, v25
	v_exp_f32_e32 v26, v26
	v_exp_f32_e32 v27, v27
	v_add_f32_e32 v24, 1.0, v24
	v_add_f32_e32 v25, 1.0, v25
	v_add_f32_e32 v26, 1.0, v26
	v_add_f32_e32 v27, 1.0, v27
	v_rcp_f32_e32 v24, v24
	v_rcp_f32_e32 v25, v25
	v_rcp_f32_e32 v26, v26
	v_rcp_f32_e32 v27, v27
	v_mul_f32_e32 v20, v20, v24
	v_mul_f32_e32 v21, v21, v25
	v_mul_f32_e32 v22, v22, v26
	v_mul_f32_e32 v23, v23, v27
	v_cvt_pk_bf16_f32 v20, v20, v20
	v_cvt_pk_bf16_f32 v21, v21, v21
	v_cvt_pk_bf16_f32 v22, v22, v22
	v_cvt_pk_bf16_f32 v23, v23, v23
	ds_write_b16 v19, v20 offset:11968
	ds_write_b16 v19, v21 offset:12240
	ds_write_b16 v19, v22 offset:12512
	ds_write_b16 v19, v23 offset:12784
	s_waitcnt vmcnt(12)
; DI bf16_t f2bf(float f) { return (bf16_t)(pk2(f, f) & 0xffffu); }
; DI float silu_(float x) { return x * sigm(x); }
; DI void prep_delta(LAS unsigned char* lds, const Params& P, int l, int unit) {
;     ...
; #pragma unroll
;             for (int t = 0; t < 64; ++t) { const float x0 = px[(size_t)t * LDP]; const float y = silu_(w0 * x3 + w1 * x2 + w2 * x1 + w3 * x0); x3 = x2; x2 = x1; x1 = x0;
;                 if (part == 0) qf[t * 136 + j] = f2bf(y); else rhs[t * 256 + (part - 1) * 128 + j] = y; }
	v_mul_f32_e32 v20, v4, v101
	v_mul_f32_e32 v21, v4, v102
	v_mul_f32_e32 v22, v4, v103
	v_mul_f32_e32 v23, v4, v104
	v_fmac_f32_e32 v20, v5, v102
	v_fmac_f32_e32 v21, v5, v103
	v_fmac_f32_e32 v22, v5, v104
	v_fmac_f32_e32 v23, v5, v105
	v_fmac_f32_e32 v20, v7, v103
	v_fmac_f32_e32 v21, v7, v104
	v_fmac_f32_e32 v22, v7, v105
	v_fmac_f32_e32 v23, v7, v106
	v_fmac_f32_e32 v20, v9, v104
	v_fmac_f32_e32 v21, v9, v105
	v_fmac_f32_e32 v22, v9, v106
	v_fmac_f32_e32 v23, v9, v107
	v_mul_f32_e32 v24, 0xbfb8aa3b, v20
	v_mul_f32_e32 v25, 0xbfb8aa3b, v21
	v_mul_f32_e32 v26, 0xbfb8aa3b, v22
	v_mul_f32_e32 v27, 0xbfb8aa3b, v23
	v_exp_f32_e32 v24, v24
	v_exp_f32_e32 v25, v25
	v_exp_f32_e32 v26, v26
	v_exp_f32_e32 v27, v27
	v_add_f32_e32 v24, 1.0, v24
	v_add_f32_e32 v25, 1.0, v25
	v_add_f32_e32 v26, 1.0, v26
	v_add_f32_e32 v27, 1.0, v27
	v_rcp_f32_e32 v24, v24
	v_rcp_f32_e32 v25, v25
	v_rcp_f32_e32 v26, v26
	v_rcp_f32_e32 v27, v27
	v_mul_f32_e32 v20, v20, v24
	v_mul_f32_e32 v21, v21, v25
	v_mul_f32_e32 v22, v22, v26
	v_mul_f32_e32 v23, v23, v27
	v_cvt_pk_bf16_f32 v20, v20, v20
	v_cvt_pk_bf16_f32 v21, v21, v21
	v_cvt_pk_bf16_f32 v22, v22, v22
	v_cvt_pk_bf16_f32 v23, v23, v23
	ds_write_b16 v19, v20 offset:13056
	ds_write_b16 v19, v21 offset:13328
	ds_write_b16 v19, v22 offset:13600
	ds_write_b16 v19, v23 offset:13872
	s_waitcnt vmcnt(8)
	v_mul_f32_e32 v20, v4, v105
	v_mul_f32_e32 v21, v4, v106
	v_mul_f32_e32 v22, v4, v107
	v_mul_f32_e32 v23, v4, v108
	v_fmac_f32_e32 v20, v5, v106
	v_fmac_f32_e32 v21, v5, v107
	v_fmac_f32_e32 v22, v5, v108
	v_fmac_f32_e32 v23, v5, v109
	v_fmac_f32_e32 v20, v7, v107
	v_fmac_f32_e32 v21, v7, v108
	v_fmac_f32_e32 v22, v7, v109
	v_fmac_f32_e32 v23, v7, v110
	v_fmac_f32_e32 v20, v9, v108
	v_fmac_f32_e32 v21, v9, v109
	v_fmac_f32_e32 v22, v9, v110
	v_fmac_f32_e32 v23, v9, v111
	v_mul_f32_e32 v24, 0xbfb8aa3b, v20
	v_mul_f32_e32 v25, 0xbfb8aa3b, v21
	v_mul_f32_e32 v26, 0xbfb8aa3b, v22
	v_mul_f32_e32 v27, 0xbfb8aa3b, v23
	v_exp_f32_e32 v24, v24
	v_exp_f32_e32 v25, v25
	v_exp_f32_e32 v26, v26
	v_exp_f32_e32 v27, v27
	v_add_f32_e32 v24, 1.0, v24
	v_add_f32_e32 v25, 1.0, v25
	v_add_f32_e32 v26, 1.0, v26
	v_add_f32_e32 v27, 1.0, v27
	v_rcp_f32_e32 v24, v24
	v_rcp_f32_e32 v25, v25
	v_rcp_f32_e32 v26, v26
	v_rcp_f32_e32 v27, v27
	v_mul_f32_e32 v20, v20, v24
	v_mul_f32_e32 v21, v21, v25
	v_mul_f32_e32 v22, v22, v26
	v_mul_f32_e32 v23, v23, v27
	v_cvt_pk_bf16_f32 v20, v20, v20
	v_cvt_pk_bf16_f32 v21, v21, v21
	v_cvt_pk_bf16_f32 v22, v22, v22
	v_cvt_pk_bf16_f32 v23, v23, v23
	ds_write_b16 v19, v20 offset:14144
	ds_write_b16 v19, v21 offset:14416
	ds_write_b16 v19, v22 offset:14688
	ds_write_b16 v19, v23 offset:14960
	s_waitcnt vmcnt(4)
	v_mul_f32_e32 v20, v4, v109
	v_mul_f32_e32 v21, v4, v110
	v_mul_f32_e32 v22, v4, v111
	v_mul_f32_e32 v23, v4, v112
	v_fmac_f32_e32 v20, v5, v110
	v_fmac_f32_e32 v21, v5, v111
	v_fmac_f32_e32 v22, v5, v112
	v_fmac_f32_e32 v23, v5, v113
	v_fmac_f32_e32 v20, v7, v111
	v_fmac_f32_e32 v21, v7, v112
	v_fmac_f32_e32 v22, v7, v113
	v_fmac_f32_e32 v23, v7, v114
	v_fmac_f32_e32 v20, v9, v112
	v_fmac_f32_e32 v21, v9, v113
	v_fmac_f32_e32 v22, v9, v114
	v_fmac_f32_e32 v23, v9, v115
	v_mul_f32_e32 v24, 0xbfb8aa3b, v20
	v_mul_f32_e32 v25, 0xbfb8aa3b, v21
	v_mul_f32_e32 v26, 0xbfb8aa3b, v22
	v_mul_f32_e32 v27, 0xbfb8aa3b, v23
	v_exp_f32_e32 v24, v24
	v_exp_f32_e32 v25, v25
	v_exp_f32_e32 v26, v26
	v_exp_f32_e32 v27, v27
	v_add_f32_e32 v24, 1.0, v24
	v_add_f32_e32 v25, 1.0, v25
	v_add_f32_e32 v26, 1.0, v26
	v_add_f32_e32 v27, 1.0, v27
	v_rcp_f32_e32 v24, v24
	v_rcp_f32_e32 v25, v25
	v_rcp_f32_e32 v26, v26
	v_rcp_f32_e32 v27, v27
	v_mul_f32_e32 v20, v20, v24
	v_mul_f32_e32 v21, v21, v25
	v_mul_f32_e32 v22, v22, v26
	v_mul_f32_e32 v23, v23, v27
	v_cvt_pk_bf16_f32 v20, v20, v20
	v_cvt_pk_bf16_f32 v21, v21, v21
	v_cvt_pk_bf16_f32 v22, v22, v22
	v_cvt_pk_bf16_f32 v23, v23, v23
	ds_write_b16 v19, v20 offset:15232
	ds_write_b16 v19, v21 offset:15504
	ds_write_b16 v19, v22 offset:15776
	ds_write_b16 v19, v23 offset:16048
	s_waitcnt vmcnt(0)
	v_mul_f32_e32 v20, v4, v113
	v_mul_f32_e32 v21, v4, v114
	v_mul_f32_e32 v22, v4, v115
	v_mul_f32_e32 v23, v4, v116
	v_fmac_f32_e32 v20, v5, v114
	v_fmac_f32_e32 v21, v5, v115
	v_fmac_f32_e32 v22, v5, v116
	v_fmac_f32_e32 v23, v5, v117
	v_fmac_f32_e32 v20, v7, v115
	v_fmac_f32_e32 v21, v7, v116
	v_fmac_f32_e32 v22, v7, v117
	v_fmac_f32_e32 v23, v7, v118
	v_fmac_f32_e32 v20, v9, v116
	v_fmac_f32_e32 v21, v9, v117
	v_fmac_f32_e32 v22, v9, v118
	v_fmac_f32_e32 v23, v9, v119
	v_mul_f32_e32 v24, 0xbfb8aa3b, v20
	v_mul_f32_e32 v25, 0xbfb8aa3b, v21
	v_mul_f32_e32 v26, 0xbfb8aa3b, v22
	v_mul_f32_e32 v27, 0xbfb8aa3b, v23
	v_exp_f32_e32 v24, v24
	v_exp_f32_e32 v25, v25
	v_exp_f32_e32 v26, v26
	v_exp_f32_e32 v27, v27
	v_add_f32_e32 v24, 1.0, v24
	v_add_f32_e32 v25, 1.0, v25
	v_add_f32_e32 v26, 1.0, v26
	v_add_f32_e32 v27, 1.0, v27
	v_rcp_f32_e32 v24, v24
	v_rcp_f32_e32 v25, v25
	v_rcp_f32_e32 v26, v26
	v_rcp_f32_e32 v27, v27
	v_mul_f32_e32 v20, v20, v24
	v_mul_f32_e32 v21, v21, v25
	v_mul_f32_e32 v22, v22, v26
	v_mul_f32_e32 v23, v23, v27
	v_cvt_pk_bf16_f32 v20, v20, v20
	v_cvt_pk_bf16_f32 v21, v21, v21
	v_cvt_pk_bf16_f32 v22, v22, v22
	v_cvt_pk_bf16_f32 v23, v23, v23
	ds_write_b16 v19, v20 offset:16320
	ds_write_b16 v19, v21 offset:16592
	ds_write_b16 v19, v22 offset:16864
	ds_write_b16 v19, v23 offset:17136
	s_branch .LBB0_1099
; DI bf16_t f2bf(float f) { return (bf16_t)(pk2(f, f) & 0xffffu); }
; DI float silu_(float x) { return x * sigm(x); }
; DI void prep_delta(LAS unsigned char* lds, const Params& P, int l, int unit) {
;     ...
; #pragma unroll
;             for (int t = 0; t < 64; ++t) { const float x0 = px[(size_t)t * LDP]; const float y = silu_(w0 * x3 + w1 * x2 + w2 * x1 + w3 * x0); x3 = x2; x2 = x1; x1 = x0;
;                 if (part == 0) qf[t * 136 + j] = f2bf(y); else rhs[t * 256 + (part - 1) * 128 + j] = y; }
.Lconv_rhs_part:
	v_lshlrev_b32_e32 v19, 2, v6
	v_add_u32_e32 v19, 0xfffffe00, v19
	s_waitcnt vmcnt(36)
	v_mul_f32_e32 v20, v4, v10
	v_mul_f32_e32 v21, v4, v11
	v_mul_f32_e32 v22, v4, v15
	v_mul_f32_e32 v23, v4, v56
	v_fmac_f32_e32 v20, v5, v11
	v_fmac_f32_e32 v21, v5, v15
	v_fmac_f32_e32 v22, v5, v56
	v_fmac_f32_e32 v23, v5, v57
	v_fmac_f32_e32 v20, v7, v15
	v_fmac_f32_e32 v21, v7, v56
	v_fmac_f32_e32 v22, v7, v57
	v_fmac_f32_e32 v23, v7, v58
	v_fmac_f32_e32 v20, v9, v56
	v_fmac_f32_e32 v21, v9, v57
	v_fmac_f32_e32 v22, v9, v58
	v_fmac_f32_e32 v23, v9, v59
	v_mul_f32_e32 v24, 0xbfb8aa3b, v20
	v_mul_f32_e32 v25, 0xbfb8aa3b, v21
	v_mul_f32_e32 v26, 0xbfb8aa3b, v22
	v_mul_f32_e32 v27, 0xbfb8aa3b, v23
	v_exp_f32_e32 v24, v24
	v_exp_f32_e32 v25, v25
	v_exp_f32_e32 v26, v26
	v_exp_f32_e32 v27, v27
	v_add_f32_e32 v24, 1.0, v24
	v_add_f32_e32 v25, 1.0, v25
	v_add_f32_e32 v26, 1.0, v26
	v_add_f32_e32 v27, 1.0, v27
	v_rcp_f32_e32 v24, v24
	v_rcp_f32_e32 v25, v25
	v_rcp_f32_e32 v26, v26
	v_rcp_f32_e32 v27, v27
	v_mul_f32_e32 v20, v20, v24
	v_mul_f32_e32 v21, v21, v25
	v_mul_f32_e32 v22, v22, v26
	v_mul_f32_e32 v23, v23, v27
	ds_write_b32 v19, v20 offset:0
	ds_write_b32 v19, v21 offset:1024
	ds_write_b32 v19, v22 offset:2048
	ds_write_b32 v19, v23 offset:3072
	s_waitcnt vmcnt(32)
	v_mul_f32_e32 v20, v4, v57
	v_mul_f32_e32 v21, v4, v58
	v_mul_f32_e32 v22, v4, v59
	v_mul_f32_e32 v23, v4, v60
	v_fmac_f32_e32 v20, v5, v58
	v_fmac_f32_e32 v21, v5, v59
	v_fmac_f32_e32 v22, v5, v60
	v_fmac_f32_e32 v23, v5, v61
	v_fmac_f32_e32 v20, v7, v59
	v_fmac_f32_e32 v21, v7, v60
	v_fmac_f32_e32 v22, v7, v61
	v_fmac_f32_e32 v23, v7, v62
	v_fmac_f32_e32 v20, v9, v60
	v_fmac_f32_e32 v21, v9, v61
	v_fmac_f32_e32 v22, v9, v62
	v_fmac_f32_e32 v23, v9, v63
	v_mul_f32_e32 v24, 0xbfb8aa3b, v20
	v_mul_f32_e32 v25, 0xbfb8aa3b, v21
	v_mul_f32_e32 v26, 0xbfb8aa3b, v22
	v_mul_f32_e32 v27, 0xbfb8aa3b, v23
	v_exp_f32_e32 v24, v24
	v_exp_f32_e32 v25, v25
	v_exp_f32_e32 v26, v26
	v_exp_f32_e32 v27, v27
	v_add_f32_e32 v24, 1.0, v24
	v_add_f32_e32 v25, 1.0, v25
	v_add_f32_e32 v26, 1.0, v26
	v_add_f32_e32 v27, 1.0, v27
	v_rcp_f32_e32 v24, v24
	v_rcp_f32_e32 v25, v25
	v_rcp_f32_e32 v26, v26
	v_rcp_f32_e32 v27, v27
	v_mul_f32_e32 v20, v20, v24
	v_mul_f32_e32 v21, v21, v25
	v_mul_f32_e32 v22, v22, v26
	v_mul_f32_e32 v23, v23, v27
	ds_write_b32 v19, v20 offset:4096
	ds_write_b32 v19, v21 offset:5120
	ds_write_b32 v19, v22 offset:6144
	ds_write_b32 v19, v23 offset:7168
	s_waitcnt vmcnt(28)
	v_mul_f32_e32 v20, v4, v61
	v_mul_f32_e32 v21, v4, v62
	v_mul_f32_e32 v22, v4, v63
	v_mul_f32_e32 v23, v4, v64
	v_fmac_f32_e32 v20, v5, v62
	v_fmac_f32_e32 v21, v5, v63
	v_fmac_f32_e32 v22, v5, v64
	v_fmac_f32_e32 v23, v5, v65
	v_fmac_f32_e32 v20, v7, v63
	v_fmac_f32_e32 v21, v7, v64
	v_fmac_f32_e32 v22, v7, v65
	v_fmac_f32_e32 v23, v7, v66
	v_fmac_f32_e32 v20, v9, v64
	v_fmac_f32_e32 v21, v9, v65
	v_fmac_f32_e32 v22, v9, v66
	v_fmac_f32_e32 v23, v9, v67
	v_mul_f32_e32 v24, 0xbfb8aa3b, v20
	v_mul_f32_e32 v25, 0xbfb8aa3b, v21
	v_mul_f32_e32 v26, 0xbfb8aa3b, v22
	v_mul_f32_e32 v27, 0xbfb8aa3b, v23
	v_exp_f32_e32 v24, v24
	v_exp_f32_e32 v25, v25
	v_exp_f32_e32 v26, v26
	v_exp_f32_e32 v27, v27
	v_add_f32_e32 v24, 1.0, v24
	v_add_f32_e32 v25, 1.0, v25
	v_add_f32_e32 v26, 1.0, v26
	v_add_f32_e32 v27, 1.0, v27
	v_rcp_f32_e32 v24, v24
	v_rcp_f32_e32 v25, v25
	v_rcp_f32_e32 v26, v26
	v_rcp_f32_e32 v27, v27
	v_mul_f32_e32 v20, v20, v24
	v_mul_f32_e32 v21, v21, v25
	v_mul_f32_e32 v22, v22, v26
	v_mul_f32_e32 v23, v23, v27
	ds_write_b32 v19, v20 offset:8192
	ds_write_b32 v19, v21 offset:9216
	ds_write_b32 v19, v22 offset:10240
	ds_write_b32 v19, v23 offset:11264
	s_waitcnt vmcnt(24)
	v_mul_f32_e32 v20, v4, v65
	v_mul_f32_e32 v21, v4, v66
	v_mul_f32_e32 v22, v4, v67
	v_mul_f32_e32 v23, v4, v68
	v_fmac_f32_e32 v20, v5, v66
	v_fmac_f32_e32 v21, v5, v67
	v_fmac_f32_e32 v22, v5, v68
	v_fmac_f32_e32 v23, v5, v69
	v_fmac_f32_e32 v20, v7, v67
	v_fmac_f32_e32 v21, v7, v68
	v_fmac_f32_e32 v22, v7, v69
	v_fmac_f32_e32 v23, v7, v70
	v_fmac_f32_e32 v20, v9, v68
	v_fmac_f32_e32 v21, v9, v69
	v_fmac_f32_e32 v22, v9, v70
	v_fmac_f32_e32 v23, v9, v71
	v_mul_f32_e32 v24, 0xbfb8aa3b, v20
	v_mul_f32_e32 v25, 0xbfb8aa3b, v21
	v_mul_f32_e32 v26, 0xbfb8aa3b, v22
	v_mul_f32_e32 v27, 0xbfb8aa3b, v23
	v_exp_f32_e32 v24, v24
	v_exp_f32_e32 v25, v25
	v_exp_f32_e32 v26, v26
	v_exp_f32_e32 v27, v27
	v_add_f32_e32 v24, 1.0, v24
	v_add_f32_e32 v25, 1.0, v25
	v_add_f32_e32 v26, 1.0, v26
	v_add_f32_e32 v27, 1.0, v27
	v_rcp_f32_e32 v24, v24
	v_rcp_f32_e32 v25, v25
	v_rcp_f32_e32 v26, v26
	v_rcp_f32_e32 v27, v27
	v_mul_f32_e32 v20, v20, v24
	v_mul_f32_e32 v21, v21, v25
	v_mul_f32_e32 v22, v22, v26
	v_mul_f32_e32 v23, v23, v27
	ds_write_b32 v19, v20 offset:12288
	ds_write_b32 v19, v21 offset:13312
	ds_write_b32 v19, v22 offset:14336
	ds_write_b32 v19, v23 offset:15360
	global_load_dword v96, v18, s[6:7]
	s_add_u32 s6, s6, 0x6800
	s_addc_u32 s7, s7, 0
	global_load_dword v97, v18, s[6:7]
	s_add_u32 s6, s6, 0x6800
	s_addc_u32 s7, s7, 0
	global_load_dword v98, v18, s[6:7]
	s_add_u32 s6, s6, 0x6800
	s_addc_u32 s7, s7, 0
	global_load_dword v99, v18, s[6:7]
	s_add_u32 s6, s6, 0x6800
	s_addc_u32 s7, s7, 0
	global_load_dword v100, v18, s[6:7]
	s_add_u32 s6, s6, 0x6800
	s_addc_u32 s7, s7, 0
	global_load_dword v101, v18, s[6:7]
	s_add_u32 s6, s6, 0x6800
	s_addc_u32 s7, s7, 0
	global_load_dword v102, v18, s[6:7]
	s_add_u32 s6, s6, 0x6800
	s_addc_u32 s7, s7, 0
	global_load_dword v103, v18, s[6:7]
	s_add_u32 s6, s6, 0x6800
	s_addc_u32 s7, s7, 0
	global_load_dword v104, v18, s[6:7]
	s_add_u32 s6, s6, 0x6800
	s_addc_u32 s7, s7, 0
	global_load_dword v105, v18, s[6:7]
	s_add_u32 s6, s6, 0x6800
	s_addc_u32 s7, s7, 0
	global_load_dword v106, v18, s[6:7]
	s_add_u32 s6, s6, 0x6800
	s_addc_u32 s7, s7, 0
	global_load_dword v107, v18, s[6:7]
	s_add_u32 s6, s6, 0x6800
	s_addc_u32 s7, s7, 0
	global_load_dword v108, v18, s[6:7]
	s_add_u32 s6, s6, 0x6800
	s_addc_u32 s7, s7, 0
	global_load_dword v109, v18, s[6:7]
	s_add_u32 s6, s6, 0x6800
	s_addc_u32 s7, s7, 0
	global_load_dword v110, v18, s[6:7]
	s_add_u32 s6, s6, 0x6800
	s_addc_u32 s7, s7, 0
	global_load_dword v111, v18, s[6:7]
	s_add_u32 s6, s6, 0x6800
	s_addc_u32 s7, s7, 0
	global_load_dword v112, v18, s[6:7]
	s_add_u32 s6, s6, 0x6800
	s_addc_u32 s7, s7, 0
	global_load_dword v113, v18, s[6:7]
	s_add_u32 s6, s6, 0x6800
	s_addc_u32 s7, s7, 0
	global_load_dword v114, v18, s[6:7]
	s_add_u32 s6, s6, 0x6800
	s_addc_u32 s7, s7, 0
	global_load_dword v115, v18, s[6:7]
	s_add_u32 s6, s6, 0x6800
	s_addc_u32 s7, s7, 0
	global_load_dword v116, v18, s[6:7]
	s_add_u32 s6, s6, 0x6800
	s_addc_u32 s7, s7, 0
	global_load_dword v117, v18, s[6:7]
	s_add_u32 s6, s6, 0x6800
	s_addc_u32 s7, s7, 0
	global_load_dword v118, v18, s[6:7]
	s_add_u32 s6, s6, 0x6800
	s_addc_u32 s7, s7, 0
	global_load_dword v119, v18, s[6:7]
	s_add_u32 s6, s6, 0x6800
	s_addc_u32 s7, s7, 0
	s_waitcnt vmcnt(44)
; DI bf16_t f2bf(float f) { return (bf16_t)(pk2(f, f) & 0xffffu); }
; DI float silu_(float x) { return x * sigm(x); }
; DI void prep_delta(LAS unsigned char* lds, const Params& P, int l, int unit) {
;     ...
; #pragma unroll
;             for (int t = 0; t < 64; ++t) { const float x0 = px[(size_t)t * LDP]; const float y = silu_(w0 * x3 + w1 * x2 + w2 * x1 + w3 * x0); x3 = x2; x2 = x1; x1 = x0;
;                 if (part == 0) qf[t * 136 + j] = f2bf(y); else rhs[t * 256 + (part - 1) * 128 + j] = y; }
	v_mul_f32_e32 v20, v4, v69
	v_mul_f32_e32 v21, v4, v70
	v_mul_f32_e32 v22, v4, v71
	v_mul_f32_e32 v23, v4, v72
	v_fmac_f32_e32 v20, v5, v70
	v_fmac_f32_e32 v21, v5, v71
	v_fmac_f32_e32 v22, v5, v72
	v_fmac_f32_e32 v23, v5, v73
	v_fmac_f32_e32 v20, v7, v71
	v_fmac_f32_e32 v21, v7, v72
	v_fmac_f32_e32 v22, v7, v73
	v_fmac_f32_e32 v23, v7, v74
	v_fmac_f32_e32 v20, v9, v72
	v_fmac_f32_e32 v21, v9, v73
	v_fmac_f32_e32 v22, v9, v74
	v_fmac_f32_e32 v23, v9, v75
	v_mul_f32_e32 v24, 0xbfb8aa3b, v20
	v_mul_f32_e32 v25, 0xbfb8aa3b, v21
	v_mul_f32_e32 v26, 0xbfb8aa3b, v22
	v_mul_f32_e32 v27, 0xbfb8aa3b, v23
	v_exp_f32_e32 v24, v24
	v_exp_f32_e32 v25, v25
	v_exp_f32_e32 v26, v26
	v_exp_f32_e32 v27, v27
	v_add_f32_e32 v24, 1.0, v24
	v_add_f32_e32 v25, 1.0, v25
	v_add_f32_e32 v26, 1.0, v26
	v_add_f32_e32 v27, 1.0, v27
	v_rcp_f32_e32 v24, v24
	v_rcp_f32_e32 v25, v25
	v_rcp_f32_e32 v26, v26
	v_rcp_f32_e32 v27, v27
	v_mul_f32_e32 v20, v20, v24
	v_mul_f32_e32 v21, v21, v25
	v_mul_f32_e32 v22, v22, v26
	v_mul_f32_e32 v23, v23, v27
	ds_write_b32 v19, v20 offset:16384
	ds_write_b32 v19, v21 offset:17408
	ds_write_b32 v19, v22 offset:18432
	ds_write_b32 v19, v23 offset:19456
	s_waitcnt vmcnt(40)
	v_mul_f32_e32 v20, v4, v73
	v_mul_f32_e32 v21, v4, v74
	v_mul_f32_e32 v22, v4, v75
	v_mul_f32_e32 v23, v4, v76
	v_fmac_f32_e32 v20, v5, v74
	v_fmac_f32_e32 v21, v5, v75
	v_fmac_f32_e32 v22, v5, v76
	v_fmac_f32_e32 v23, v5, v77
	v_fmac_f32_e32 v20, v7, v75
	v_fmac_f32_e32 v21, v7, v76
	v_fmac_f32_e32 v22, v7, v77
	v_fmac_f32_e32 v23, v7, v78
	v_fmac_f32_e32 v20, v9, v76
	v_fmac_f32_e32 v21, v9, v77
	v_fmac_f32_e32 v22, v9, v78
	v_fmac_f32_e32 v23, v9, v79
	v_mul_f32_e32 v24, 0xbfb8aa3b, v20
	v_mul_f32_e32 v25, 0xbfb8aa3b, v21
	v_mul_f32_e32 v26, 0xbfb8aa3b, v22
	v_mul_f32_e32 v27, 0xbfb8aa3b, v23
	v_exp_f32_e32 v24, v24
	v_exp_f32_e32 v25, v25
	v_exp_f32_e32 v26, v26
	v_exp_f32_e32 v27, v27
	v_add_f32_e32 v24, 1.0, v24
	v_add_f32_e32 v25, 1.0, v25
	v_add_f32_e32 v26, 1.0, v26
	v_add_f32_e32 v27, 1.0, v27
	v_rcp_f32_e32 v24, v24
	v_rcp_f32_e32 v25, v25
	v_rcp_f32_e32 v26, v26
	v_rcp_f32_e32 v27, v27
	v_mul_f32_e32 v20, v20, v24
	v_mul_f32_e32 v21, v21, v25
	v_mul_f32_e32 v22, v22, v26
	v_mul_f32_e32 v23, v23, v27
	ds_write_b32 v19, v20 offset:20480
	ds_write_b32 v19, v21 offset:21504
	ds_write_b32 v19, v22 offset:22528
	ds_write_b32 v19, v23 offset:23552
	s_waitcnt vmcnt(36)
	v_mul_f32_e32 v20, v4, v77
	v_mul_f32_e32 v21, v4, v78
	v_mul_f32_e32 v22, v4, v79
	v_mul_f32_e32 v23, v4, v80
	v_fmac_f32_e32 v20, v5, v78
	v_fmac_f32_e32 v21, v5, v79
	v_fmac_f32_e32 v22, v5, v80
	v_fmac_f32_e32 v23, v5, v81
	v_fmac_f32_e32 v20, v7, v79
	v_fmac_f32_e32 v21, v7, v80
	v_fmac_f32_e32 v22, v7, v81
	v_fmac_f32_e32 v23, v7, v82
	v_fmac_f32_e32 v20, v9, v80
	v_fmac_f32_e32 v21, v9, v81
	v_fmac_f32_e32 v22, v9, v82
	v_fmac_f32_e32 v23, v9, v83
	v_mul_f32_e32 v24, 0xbfb8aa3b, v20
	v_mul_f32_e32 v25, 0xbfb8aa3b, v21
	v_mul_f32_e32 v26, 0xbfb8aa3b, v22
	v_mul_f32_e32 v27, 0xbfb8aa3b, v23
	v_exp_f32_e32 v24, v24
	v_exp_f32_e32 v25, v25
	v_exp_f32_e32 v26, v26
	v_exp_f32_e32 v27, v27
	v_add_f32_e32 v24, 1.0, v24
	v_add_f32_e32 v25, 1.0, v25
	v_add_f32_e32 v26, 1.0, v26
	v_add_f32_e32 v27, 1.0, v27
	v_rcp_f32_e32 v24, v24
	v_rcp_f32_e32 v25, v25
	v_rcp_f32_e32 v26, v26
	v_rcp_f32_e32 v27, v27
	v_mul_f32_e32 v20, v20, v24
	v_mul_f32_e32 v21, v21, v25
	v_mul_f32_e32 v22, v22, v26
	v_mul_f32_e32 v23, v23, v27
	ds_write_b32 v19, v20 offset:24576
	ds_write_b32 v19, v21 offset:25600
	ds_write_b32 v19, v22 offset:26624
	ds_write_b32 v19, v23 offset:27648
	s_waitcnt vmcnt(32)
	v_mul_f32_e32 v20, v4, v81
	v_mul_f32_e32 v21, v4, v82
	v_mul_f32_e32 v22, v4, v83
	v_mul_f32_e32 v23, v4, v84
	v_fmac_f32_e32 v20, v5, v82
	v_fmac_f32_e32 v21, v5, v83
	v_fmac_f32_e32 v22, v5, v84
	v_fmac_f32_e32 v23, v5, v85
	v_fmac_f32_e32 v20, v7, v83
	v_fmac_f32_e32 v21, v7, v84
	v_fmac_f32_e32 v22, v7, v85
	v_fmac_f32_e32 v23, v7, v86
	v_fmac_f32_e32 v20, v9, v84
	v_fmac_f32_e32 v21, v9, v85
	v_fmac_f32_e32 v22, v9, v86
	v_fmac_f32_e32 v23, v9, v87
	v_mul_f32_e32 v24, 0xbfb8aa3b, v20
	v_mul_f32_e32 v25, 0xbfb8aa3b, v21
	v_mul_f32_e32 v26, 0xbfb8aa3b, v22
	v_mul_f32_e32 v27, 0xbfb8aa3b, v23
	v_exp_f32_e32 v24, v24
	v_exp_f32_e32 v25, v25
	v_exp_f32_e32 v26, v26
	v_exp_f32_e32 v27, v27
	v_add_f32_e32 v24, 1.0, v24
	v_add_f32_e32 v25, 1.0, v25
	v_add_f32_e32 v26, 1.0, v26
	v_add_f32_e32 v27, 1.0, v27
	v_rcp_f32_e32 v24, v24
	v_rcp_f32_e32 v25, v25
	v_rcp_f32_e32 v26, v26
	v_rcp_f32_e32 v27, v27
	v_mul_f32_e32 v20, v20, v24
	v_mul_f32_e32 v21, v21, v25
	v_mul_f32_e32 v22, v22, v26
	v_mul_f32_e32 v23, v23, v27
	ds_write_b32 v19, v20 offset:28672
	ds_write_b32 v19, v21 offset:29696
	ds_write_b32 v19, v22 offset:30720
	ds_write_b32 v19, v23 offset:31744
	s_waitcnt vmcnt(28)
	v_mul_f32_e32 v20, v4, v85
	v_mul_f32_e32 v21, v4, v86
	v_mul_f32_e32 v22, v4, v87
	v_mul_f32_e32 v23, v4, v88
	v_fmac_f32_e32 v20, v5, v86
	v_fmac_f32_e32 v21, v5, v87
	v_fmac_f32_e32 v22, v5, v88
	v_fmac_f32_e32 v23, v5, v89
	v_fmac_f32_e32 v20, v7, v87
	v_fmac_f32_e32 v21, v7, v88
	v_fmac_f32_e32 v22, v7, v89
	v_fmac_f32_e32 v23, v7, v90
	v_fmac_f32_e32 v20, v9, v88
	v_fmac_f32_e32 v21, v9, v89
	v_fmac_f32_e32 v22, v9, v90
	v_fmac_f32_e32 v23, v9, v91
	v_mul_f32_e32 v24, 0xbfb8aa3b, v20
	v_mul_f32_e32 v25, 0xbfb8aa3b, v21
	v_mul_f32_e32 v26, 0xbfb8aa3b, v22
	v_mul_f32_e32 v27, 0xbfb8aa3b, v23
	v_exp_f32_e32 v24, v24
	v_exp_f32_e32 v25, v25
	v_exp_f32_e32 v26, v26
	v_exp_f32_e32 v27, v27
	v_add_f32_e32 v24, 1.0, v24
	v_add_f32_e32 v25, 1.0, v25
	v_add_f32_e32 v26, 1.0, v26
	v_add_f32_e32 v27, 1.0, v27
	v_rcp_f32_e32 v24, v24
	v_rcp_f32_e32 v25, v25
	v_rcp_f32_e32 v26, v26
	v_rcp_f32_e32 v27, v27
	v_mul_f32_e32 v20, v20, v24
	v_mul_f32_e32 v21, v21, v25
	v_mul_f32_e32 v22, v22, v26
	v_mul_f32_e32 v23, v23, v27
	ds_write_b32 v19, v20 offset:32768
	ds_write_b32 v19, v21 offset:33792
	ds_write_b32 v19, v22 offset:34816
	ds_write_b32 v19, v23 offset:35840
	s_waitcnt vmcnt(24)
; DI bf16_t f2bf(float f) { return (bf16_t)(pk2(f, f) & 0xffffu); }
; DI float silu_(float x) { return x * sigm(x); }
; DI void prep_delta(LAS unsigned char* lds, const Params& P, int l, int unit) {
;     ...
; #pragma unroll
;             for (int t = 0; t < 64; ++t) { const float x0 = px[(size_t)t * LDP]; const float y = silu_(w0 * x3 + w1 * x2 + w2 * x1 + w3 * x0); x3 = x2; x2 = x1; x1 = x0;
;                 if (part == 0) qf[t * 136 + j] = f2bf(y); else rhs[t * 256 + (part - 1) * 128 + j] = y; }
	v_mul_f32_e32 v20, v4, v89
	v_mul_f32_e32 v21, v4, v90
	v_mul_f32_e32 v22, v4, v91
	v_mul_f32_e32 v23, v4, v92
	v_fmac_f32_e32 v20, v5, v90
	v_fmac_f32_e32 v21, v5, v91
	v_fmac_f32_e32 v22, v5, v92
	v_fmac_f32_e32 v23, v5, v93
	v_fmac_f32_e32 v20, v7, v91
	v_fmac_f32_e32 v21, v7, v92
	v_fmac_f32_e32 v22, v7, v93
	v_fmac_f32_e32 v23, v7, v94
	v_fmac_f32_e32 v20, v9, v92
	v_fmac_f32_e32 v21, v9, v93
	v_fmac_f32_e32 v22, v9, v94
	v_fmac_f32_e32 v23, v9, v95
	v_mul_f32_e32 v24, 0xbfb8aa3b, v20
	v_mul_f32_e32 v25, 0xbfb8aa3b, v21
	v_mul_f32_e32 v26, 0xbfb8aa3b, v22
	v_mul_f32_e32 v27, 0xbfb8aa3b, v23
	v_exp_f32_e32 v24, v24
	v_exp_f32_e32 v25, v25
	v_exp_f32_e32 v26, v26
	v_exp_f32_e32 v27, v27
	v_add_f32_e32 v24, 1.0, v24
	v_add_f32_e32 v25, 1.0, v25
	v_add_f32_e32 v26, 1.0, v26
	v_add_f32_e32 v27, 1.0, v27
	v_rcp_f32_e32 v24, v24
	v_rcp_f32_e32 v25, v25
	v_rcp_f32_e32 v26, v26
	v_rcp_f32_e32 v27, v27
	v_mul_f32_e32 v20, v20, v24
	v_mul_f32_e32 v21, v21, v25
	v_mul_f32_e32 v22, v22, v26
	v_mul_f32_e32 v23, v23, v27
	ds_write_b32 v19, v20 offset:36864
	ds_write_b32 v19, v21 offset:37888
	ds_write_b32 v19, v22 offset:38912
	ds_write_b32 v19, v23 offset:39936
	s_waitcnt vmcnt(20)
	v_mul_f32_e32 v20, v4, v93
	v_mul_f32_e32 v21, v4, v94
	v_mul_f32_e32 v22, v4, v95
	v_mul_f32_e32 v23, v4, v96
	v_fmac_f32_e32 v20, v5, v94
	v_fmac_f32_e32 v21, v5, v95
	v_fmac_f32_e32 v22, v5, v96
	v_fmac_f32_e32 v23, v5, v97
	v_fmac_f32_e32 v20, v7, v95
	v_fmac_f32_e32 v21, v7, v96
	v_fmac_f32_e32 v22, v7, v97
	v_fmac_f32_e32 v23, v7, v98
	v_fmac_f32_e32 v20, v9, v96
	v_fmac_f32_e32 v21, v9, v97
	v_fmac_f32_e32 v22, v9, v98
	v_fmac_f32_e32 v23, v9, v99
	v_mul_f32_e32 v24, 0xbfb8aa3b, v20
	v_mul_f32_e32 v25, 0xbfb8aa3b, v21
	v_mul_f32_e32 v26, 0xbfb8aa3b, v22
	v_mul_f32_e32 v27, 0xbfb8aa3b, v23
	v_exp_f32_e32 v24, v24
	v_exp_f32_e32 v25, v25
	v_exp_f32_e32 v26, v26
	v_exp_f32_e32 v27, v27
	v_add_f32_e32 v24, 1.0, v24
	v_add_f32_e32 v25, 1.0, v25
	v_add_f32_e32 v26, 1.0, v26
	v_add_f32_e32 v27, 1.0, v27
	v_rcp_f32_e32 v24, v24
	v_rcp_f32_e32 v25, v25
	v_rcp_f32_e32 v26, v26
	v_rcp_f32_e32 v27, v27
	v_mul_f32_e32 v20, v20, v24
	v_mul_f32_e32 v21, v21, v25
	v_mul_f32_e32 v22, v22, v26
	v_mul_f32_e32 v23, v23, v27
	ds_write_b32 v19, v20 offset:40960
	ds_write_b32 v19, v21 offset:41984
	ds_write_b32 v19, v22 offset:43008
	ds_write_b32 v19, v23 offset:44032
	s_waitcnt vmcnt(16)
	v_mul_f32_e32 v20, v4, v97
	v_mul_f32_e32 v21, v4, v98
	v_mul_f32_e32 v22, v4, v99
	v_mul_f32_e32 v23, v4, v100
	v_fmac_f32_e32 v20, v5, v98
	v_fmac_f32_e32 v21, v5, v99
	v_fmac_f32_e32 v22, v5, v100
	v_fmac_f32_e32 v23, v5, v101
	v_fmac_f32_e32 v20, v7, v99
	v_fmac_f32_e32 v21, v7, v100
	v_fmac_f32_e32 v22, v7, v101
	v_fmac_f32_e32 v23, v7, v102
	v_fmac_f32_e32 v20, v9, v100
	v_fmac_f32_e32 v21, v9, v101
	v_fmac_f32_e32 v22, v9, v102
	v_fmac_f32_e32 v23, v9, v103
	v_mul_f32_e32 v24, 0xbfb8aa3b, v20
	v_mul_f32_e32 v25, 0xbfb8aa3b, v21
	v_mul_f32_e32 v26, 0xbfb8aa3b, v22
	v_mul_f32_e32 v27, 0xbfb8aa3b, v23
	v_exp_f32_e32 v24, v24
	v_exp_f32_e32 v25, v25
	v_exp_f32_e32 v26, v26
	v_exp_f32_e32 v27, v27
	v_add_f32_e32 v24, 1.0, v24
	v_add_f32_e32 v25, 1.0, v25
	v_add_f32_e32 v26, 1.0, v26
	v_add_f32_e32 v27, 1.0, v27
	v_rcp_f32_e32 v24, v24
	v_rcp_f32_e32 v25, v25
	v_rcp_f32_e32 v26, v26
	v_rcp_f32_e32 v27, v27
	v_mul_f32_e32 v20, v20, v24
	v_mul_f32_e32 v21, v21, v25
	v_mul_f32_e32 v22, v22, v26
	v_mul_f32_e32 v23, v23, v27
	ds_write_b32 v19, v20 offset:45056
	ds_write_b32 v19, v21 offset:46080
	ds_write_b32 v19, v22 offset:47104
	ds_write_b32 v19, v23 offset:48128
	s_waitcnt vmcnt(12)
	v_mul_f32_e32 v20, v4, v101
	v_mul_f32_e32 v21, v4, v102
	v_mul_f32_e32 v22, v4, v103
	v_mul_f32_e32 v23, v4, v104
	v_fmac_f32_e32 v20, v5, v102
	v_fmac_f32_e32 v21, v5, v103
	v_fmac_f32_e32 v22, v5, v104
	v_fmac_f32_e32 v23, v5, v105
	v_fmac_f32_e32 v20, v7, v103
	v_fmac_f32_e32 v21, v7, v104
	v_fmac_f32_e32 v22, v7, v105
	v_fmac_f32_e32 v23, v7, v106
	v_fmac_f32_e32 v20, v9, v104
	v_fmac_f32_e32 v21, v9, v105
	v_fmac_f32_e32 v22, v9, v106
	v_fmac_f32_e32 v23, v9, v107
	v_mul_f32_e32 v24, 0xbfb8aa3b, v20
	v_mul_f32_e32 v25, 0xbfb8aa3b, v21
	v_mul_f32_e32 v26, 0xbfb8aa3b, v22
	v_mul_f32_e32 v27, 0xbfb8aa3b, v23
	v_exp_f32_e32 v24, v24
	v_exp_f32_e32 v25, v25
	v_exp_f32_e32 v26, v26
	v_exp_f32_e32 v27, v27
	v_add_f32_e32 v24, 1.0, v24
	v_add_f32_e32 v25, 1.0, v25
	v_add_f32_e32 v26, 1.0, v26
	v_add_f32_e32 v27, 1.0, v27
	v_rcp_f32_e32 v24, v24
	v_rcp_f32_e32 v25, v25
	v_rcp_f32_e32 v26, v26
	v_rcp_f32_e32 v27, v27
	v_mul_f32_e32 v20, v20, v24
	v_mul_f32_e32 v21, v21, v25
	v_mul_f32_e32 v22, v22, v26
	v_mul_f32_e32 v23, v23, v27
	ds_write_b32 v19, v20 offset:49152
	ds_write_b32 v19, v21 offset:50176
	ds_write_b32 v19, v22 offset:51200
	ds_write_b32 v19, v23 offset:52224
	s_waitcnt vmcnt(8)
; DI bf16_t f2bf(float f) { return (bf16_t)(pk2(f, f) & 0xffffu); }
; DI float silu_(float x) { return x * sigm(x); }
; DI void prep_delta(LAS unsigned char* lds, const Params& P, int l, int unit) {
;     ...
; #pragma unroll
;             for (int t = 0; t < 64; ++t) { const float x0 = px[(size_t)t * LDP]; const float y = silu_(w0 * x3 + w1 * x2 + w2 * x1 + w3 * x0); x3 = x2; x2 = x1; x1 = x0;
;                 if (part == 0) qf[t * 136 + j] = f2bf(y); else rhs[t * 256 + (part - 1) * 128 + j] = y; }
	v_mul_f32_e32 v20, v4, v105
	v_mul_f32_e32 v21, v4, v106
	v_mul_f32_e32 v22, v4, v107
	v_mul_f32_e32 v23, v4, v108
	v_fmac_f32_e32 v20, v5, v106
	v_fmac_f32_e32 v21, v5, v107
	v_fmac_f32_e32 v22, v5, v108
	v_fmac_f32_e32 v23, v5, v109
	v_fmac_f32_e32 v20, v7, v107
	v_fmac_f32_e32 v21, v7, v108
	v_fmac_f32_e32 v22, v7, v109
	v_fmac_f32_e32 v23, v7, v110
	v_fmac_f32_e32 v20, v9, v108
	v_fmac_f32_e32 v21, v9, v109
	v_fmac_f32_e32 v22, v9, v110
	v_fmac_f32_e32 v23, v9, v111
	v_mul_f32_e32 v24, 0xbfb8aa3b, v20
	v_mul_f32_e32 v25, 0xbfb8aa3b, v21
	v_mul_f32_e32 v26, 0xbfb8aa3b, v22
	v_mul_f32_e32 v27, 0xbfb8aa3b, v23
	v_exp_f32_e32 v24, v24
	v_exp_f32_e32 v25, v25
	v_exp_f32_e32 v26, v26
	v_exp_f32_e32 v27, v27
	v_add_f32_e32 v24, 1.0, v24
	v_add_f32_e32 v25, 1.0, v25
	v_add_f32_e32 v26, 1.0, v26
	v_add_f32_e32 v27, 1.0, v27
	v_rcp_f32_e32 v24, v24
	v_rcp_f32_e32 v25, v25
	v_rcp_f32_e32 v26, v26
	v_rcp_f32_e32 v27, v27
	v_mul_f32_e32 v20, v20, v24
	v_mul_f32_e32 v21, v21, v25
	v_mul_f32_e32 v22, v22, v26
	v_mul_f32_e32 v23, v23, v27
	ds_write_b32 v19, v20 offset:53248
	ds_write_b32 v19, v21 offset:54272
	ds_write_b32 v19, v22 offset:55296
	ds_write_b32 v19, v23 offset:56320
	s_waitcnt vmcnt(4)
	v_mul_f32_e32 v20, v4, v109
	v_mul_f32_e32 v21, v4, v110
	v_mul_f32_e32 v22, v4, v111
	v_mul_f32_e32 v23, v4, v112
	v_fmac_f32_e32 v20, v5, v110
	v_fmac_f32_e32 v21, v5, v111
	v_fmac_f32_e32 v22, v5, v112
	v_fmac_f32_e32 v23, v5, v113
	v_fmac_f32_e32 v20, v7, v111
	v_fmac_f32_e32 v21, v7, v112
	v_fmac_f32_e32 v22, v7, v113
	v_fmac_f32_e32 v23, v7, v114
	v_fmac_f32_e32 v20, v9, v112
	v_fmac_f32_e32 v21, v9, v113
	v_fmac_f32_e32 v22, v9, v114
	v_fmac_f32_e32 v23, v9, v115
	v_mul_f32_e32 v24, 0xbfb8aa3b, v20
	v_mul_f32_e32 v25, 0xbfb8aa3b, v21
	v_mul_f32_e32 v26, 0xbfb8aa3b, v22
	v_mul_f32_e32 v27, 0xbfb8aa3b, v23
	v_exp_f32_e32 v24, v24
	v_exp_f32_e32 v25, v25
	v_exp_f32_e32 v26, v26
	v_exp_f32_e32 v27, v27
	v_add_f32_e32 v24, 1.0, v24
	v_add_f32_e32 v25, 1.0, v25
	v_add_f32_e32 v26, 1.0, v26
	v_add_f32_e32 v27, 1.0, v27
	v_rcp_f32_e32 v24, v24
	v_rcp_f32_e32 v25, v25
	v_rcp_f32_e32 v26, v26
	v_rcp_f32_e32 v27, v27
	v_mul_f32_e32 v20, v20, v24
	v_mul_f32_e32 v21, v21, v25
	v_mul_f32_e32 v22, v22, v26
	v_mul_f32_e32 v23, v23, v27
	ds_write_b32 v19, v20 offset:57344
	ds_write_b32 v19, v21 offset:58368
	ds_write_b32 v19, v22 offset:59392
	ds_write_b32 v19, v23 offset:60416
	s_waitcnt vmcnt(0)
	v_mul_f32_e32 v20, v4, v113
	v_mul_f32_e32 v21, v4, v114
	v_mul_f32_e32 v22, v4, v115
	v_mul_f32_e32 v23, v4, v116
	v_fmac_f32_e32 v20, v5, v114
	v_fmac_f32_e32 v21, v5, v115
	v_fmac_f32_e32 v22, v5, v116
	v_fmac_f32_e32 v23, v5, v117
	v_fmac_f32_e32 v20, v7, v115
	v_fmac_f32_e32 v21, v7, v116
	v_fmac_f32_e32 v22, v7, v117
	v_fmac_f32_e32 v23, v7, v118
	v_fmac_f32_e32 v20, v9, v116
	v_fmac_f32_e32 v21, v9, v117
	v_fmac_f32_e32 v22, v9, v118
	v_fmac_f32_e32 v23, v9, v119
	v_mul_f32_e32 v24, 0xbfb8aa3b, v20
	v_mul_f32_e32 v25, 0xbfb8aa3b, v21
	v_mul_f32_e32 v26, 0xbfb8aa3b, v22
	v_mul_f32_e32 v27, 0xbfb8aa3b, v23
	v_exp_f32_e32 v24, v24
	v_exp_f32_e32 v25, v25
	v_exp_f32_e32 v26, v26
	v_exp_f32_e32 v27, v27
	v_add_f32_e32 v24, 1.0, v24
	v_add_f32_e32 v25, 1.0, v25
	v_add_f32_e32 v26, 1.0, v26
	v_add_f32_e32 v27, 1.0, v27
	v_rcp_f32_e32 v24, v24
	v_rcp_f32_e32 v25, v25
	v_rcp_f32_e32 v26, v26
	v_rcp_f32_e32 v27, v27
	v_mul_f32_e32 v20, v20, v24
	v_mul_f32_e32 v21, v21, v25
	v_mul_f32_e32 v22, v22, v26
	v_mul_f32_e32 v23, v23, v27
	ds_write_b32 v19, v20 offset:61440
	ds_write_b32 v19, v21 offset:62464
	ds_write_b32 v19, v22 offset:63488
	ds_write_b32 v19, v23 offset:64512
